# scan loop: loader gate-load wait hoisted, U/decay prefetch a full iteration ahead, W.S/q.S LDS fragment reads pipelined 5 deep; write-through (sc1) stores in P0 and P4 epilogue, nt stores in P1 epilog
# speedup vs baseline: 1.0071x; 1.0071x over previous
.LBB0_21:
	s_waitcnt vmcnt(7)
	v_mul_f32_e32 v101, v45, v45
	s_waitcnt vmcnt(6)
	v_mul_f32_e32 v106, v41, v41
	s_waitcnt vmcnt(4)
	v_pk_mul_f32 v[124:125], v[32:33], v[32:33]
	v_pk_mul_f32 v[126:127], v[36:37], v[36:37]
	v_fmac_f32_e32 v101, v44, v44
	v_fmac_f32_e32 v106, v40, v40
	v_pk_mul_f32 v[122:123], v[34:35], v[34:35]
	v_mov_b32_e32 v128, v124
	v_mov_b32_e32 v129, v126
	v_mov_b32_e32 v126, v125
	v_pk_mul_f32 v[124:125], v[38:39], v[38:39]
	v_fmac_f32_e32 v101, v46, v46
	v_fmac_f32_e32 v106, v42, v42
	v_pk_add_f32 v[126:127], v[128:129], v[126:127]
	v_mov_b32_e32 v128, v122
	v_mov_b32_e32 v129, v124
	v_fmac_f32_e32 v101, v47, v47
	v_fmac_f32_e32 v106, v43, v43
	v_pk_add_f32 v[126:127], v[128:129], v[126:127]
	v_mov_b32_e32 v124, v123
	v_add_f32_e32 v101, v101, v106
	v_pk_add_f32 v[122:123], v[124:125], v[126:127]
	s_waitcnt vmcnt(2)
	v_pk_mul_f32 v[118:119], v[88:89], v[88:89]
	v_pk_mul_f32 v[120:121], v[92:93], v[92:93]
	v_add_f32_e32 v101, v123, v101
	v_pk_mul_f32 v[114:115], v[90:91], v[90:91]
	v_pk_mul_f32 v[116:117], v[94:95], v[94:95]
	v_add_f32_e32 v101, v122, v101
	v_mov_b32_e32 v122, v118
	v_mov_b32_e32 v123, v120
	v_mov_b32_e32 v120, v119
	v_pk_add_f32 v[118:119], v[122:123], v[120:121]
	v_mov_b32_e32 v120, v114
	v_mov_b32_e32 v121, v116
	v_pk_add_f32 v[118:119], v[120:121], v[118:119]
	v_mov_b32_e32 v116, v115
	v_pk_add_f32 v[114:115], v[116:117], v[118:119]
	s_waitcnt vmcnt(0)
	v_pk_mul_f32 v[110:111], v[80:81], v[80:81]
	v_pk_mul_f32 v[112:113], v[84:85], v[84:85]
	v_add_f32_e32 v101, v115, v101
	v_pk_mul_f32 v[106:107], v[82:83], v[82:83]
	v_pk_mul_f32 v[108:109], v[86:87], v[86:87]
	v_add_f32_e32 v101, v114, v101
	v_mov_b32_e32 v114, v110
	v_mov_b32_e32 v115, v112
	v_mov_b32_e32 v112, v111
	v_pk_add_f32 v[110:111], v[114:115], v[112:113]
	v_mov_b32_e32 v112, v106
	v_mov_b32_e32 v113, v108
	v_pk_add_f32 v[110:111], v[112:113], v[110:111]
	v_mov_b32_e32 v108, v107
	v_pk_add_f32 v[106:107], v[108:109], v[110:111]
	s_add_i32 s12, s12, s34
	v_add_f32_e32 v101, v107, v101
	v_add_f32_e32 v101, v106, v101
	s_nop 1
	v_add_f32_dpp v101, v101, v101 quad_perm:[1,0,3,2] row_mask:0xf bank_mask:0xf bound_ctrl:1
	s_nop 1
	v_add_f32_dpp v101, v101, v101 quad_perm:[2,3,0,1] row_mask:0xf bank_mask:0xf bound_ctrl:1
	s_nop 1
	v_add_f32_dpp v101, v101, v101 row_half_mirror row_mask:0xf bank_mask:0xf bound_ctrl:1
	s_nop 1
	v_add_f32_dpp v101, v101, v101 row_mirror row_mask:0xf bank_mask:0xf bound_ctrl:1
	s_nop 0
	v_readlane_b32 s48, v101, 16
	v_readlane_b32 s49, v101, 48
	v_readlane_b32 s46, v101, 0
	v_readlane_b32 s47, v101, 32
	v_mov_b32_e32 v106, s48
	v_mov_b32_e32 v107, s49
	v_pk_add_f32 v[106:107], s[46:47], v[106:107]
	s_add_i32 s46, s12, 0x4000
	v_add_f32_e32 v101, v106, v107
	v_fmamk_f32 v101, v101, 0x3a000000, v99
	v_mul_f32_e32 v106, 0x4b800000, v101
	v_cmp_gt_f32_e32 vcc, s33, v101
	s_add_u32 s1, s1, s34
	s_addc_u32 s13, s13, s35
	v_cndmask_b32_e32 v101, v101, v106, vcc
	v_rsq_f32_e32 v101, v101
	s_cmpk_lt_i32 s46, 0x4010
	v_mul_f32_e32 v106, 0x45800000, v101
	v_cndmask_b32_e32 v106, v101, v106, vcc
	v_pk_mul_f32 v[32:33], v[32:33], v[106:107] op_sel_hi:[1,0]
	v_pk_mul_f32 v[34:35], v[34:35], v[106:107] op_sel_hi:[1,0]
	v_pk_mul_f32 v[32:33], v[16:17], v[32:33]
	v_pk_mul_f32 v[34:35], v[18:19], v[34:35]
	v_cvt_pk_bf16_f32 v32, v32, v33
	v_cvt_pk_bf16_f32 v33, v34, v35
	global_store_dwordx2 v[104:105], v[32:33], off offset:1536 sc1
	v_pk_mul_f32 v[32:33], v[92:93], v[106:107] op_sel_hi:[1,0]
	v_pk_mul_f32 v[34:35], v[94:95], v[106:107] op_sel_hi:[1,0]
	v_pk_mul_f32 v[32:33], v[12:13], v[32:33]
	v_pk_mul_f32 v[34:35], v[14:15], v[34:35]
	v_cvt_pk_bf16_f32 v32, v32, v33
	v_cvt_pk_bf16_f32 v33, v34, v35
	global_store_dwordx2 v[104:105], v[32:33], off offset:2048 sc1
	v_pk_mul_f32 v[32:33], v[88:89], v[106:107] op_sel_hi:[1,0]
	v_pk_mul_f32 v[34:35], v[90:91], v[106:107] op_sel_hi:[1,0]
	v_pk_mul_f32 v[32:33], v[8:9], v[32:33]
	v_pk_mul_f32 v[34:35], v[10:11], v[34:35]
	v_cvt_pk_bf16_f32 v32, v32, v33
	v_cvt_pk_bf16_f32 v33, v34, v35
	global_store_dwordx2 v[104:105], v[32:33], off offset:2560 sc1
	v_pk_mul_f32 v[32:33], v[84:85], v[106:107] op_sel_hi:[1,0]
	v_pk_mul_f32 v[34:35], v[86:87], v[106:107] op_sel_hi:[1,0]
	v_pk_mul_f32 v[32:33], v[4:5], v[32:33]
	v_pk_mul_f32 v[34:35], v[6:7], v[34:35]
	v_cvt_pk_bf16_f32 v32, v32, v33
	v_cvt_pk_bf16_f32 v33, v34, v35
	v_pk_mul_f32 v[44:45], v[44:45], v[106:107] op_sel_hi:[1,0]
	v_pk_mul_f32 v[46:47], v[46:47], v[106:107] op_sel_hi:[1,0]
	v_pk_mul_f32 v[40:41], v[40:41], v[106:107] op_sel_hi:[1,0]
	v_pk_mul_f32 v[42:43], v[42:43], v[106:107] op_sel_hi:[1,0]
	v_pk_mul_f32 v[36:37], v[36:37], v[106:107] op_sel_hi:[1,0]
	v_pk_mul_f32 v[38:39], v[38:39], v[106:107] op_sel_hi:[1,0]
	global_store_dwordx2 v[104:105], v[32:33], off offset:3072 sc1
	v_pk_mul_f32 v[32:33], v[80:81], v[106:107] op_sel_hi:[1,0]
	v_pk_mul_f32 v[34:35], v[82:83], v[106:107] op_sel_hi:[1,0]
	v_pk_mul_f32 v[44:45], v[28:29], v[44:45]
	v_pk_mul_f32 v[46:47], v[30:31], v[46:47]
	v_pk_mul_f32 v[40:41], v[24:25], v[40:41]
	v_pk_mul_f32 v[42:43], v[26:27], v[42:43]
	v_pk_mul_f32 v[36:37], v[20:21], v[36:37]
	v_pk_mul_f32 v[38:39], v[22:23], v[38:39]
	v_pk_mul_f32 v[32:33], v[0:1], v[32:33]
	v_pk_mul_f32 v[34:35], v[2:3], v[34:35]
	v_cvt_pk_bf16_f32 v44, v44, v45
	v_cvt_pk_bf16_f32 v45, v46, v47
	v_cvt_pk_bf16_f32 v40, v40, v41
	v_cvt_pk_bf16_f32 v41, v42, v43
	v_cvt_pk_bf16_f32 v36, v36, v37
	v_cvt_pk_bf16_f32 v37, v38, v39
	v_cvt_pk_bf16_f32 v32, v32, v33
	v_cvt_pk_bf16_f32 v33, v34, v35
	global_store_dwordx2 v[104:105], v[44:45], off sc1
	global_store_dwordx2 v[104:105], v[40:41], off offset:512 sc1
	global_store_dwordx2 v[104:105], v[36:37], off offset:1024 sc1
	global_store_dwordx2 v[104:105], v[32:33], off offset:3584 sc1
	v_lshl_add_u64 v[104:105], v[104:105], 0, s[4:5]
	v_mov_b32_e32 v44, v60
	v_mov_b32_e32 v45, v61
	v_mov_b32_e32 v46, v62
	v_mov_b32_e32 v47, v63
	v_mov_b32_e32 v40, v56
	v_mov_b32_e32 v41, v57
	v_mov_b32_e32 v42, v58
	v_mov_b32_e32 v43, v59
	v_mov_b32_e32 v36, v52
	v_mov_b32_e32 v37, v53
	v_mov_b32_e32 v38, v54
	v_mov_b32_e32 v39, v55
	v_mov_b32_e32 v32, v48
	v_mov_b32_e32 v33, v49
	v_mov_b32_e32 v34, v50
	v_mov_b32_e32 v35, v51
	v_mov_b32_e32 v92, v76
	v_mov_b32_e32 v93, v77
	v_mov_b32_e32 v94, v78
	v_mov_b32_e32 v95, v79
	v_mov_b32_e32 v88, v72
	v_mov_b32_e32 v89, v73
	v_mov_b32_e32 v90, v74
	v_mov_b32_e32 v91, v75
	v_mov_b32_e32 v84, v68
	v_mov_b32_e32 v85, v69
	v_mov_b32_e32 v86, v70
	v_mov_b32_e32 v87, v71
	v_mov_b32_e32 v80, v64
	v_mov_b32_e32 v81, v65
	v_mov_b32_e32 v82, v66
	v_mov_b32_e32 v83, v67
	s_cbranch_scc0 .LBB0_24

.LBB0_27:
	s_or_b64 exec, exec, s[12:13]
	v_ashrrev_i32_e32 v9, 31, v8
	v_lshlrev_b64 v[8:9], 12, v[8:9]
	s_waitcnt lgkmcnt(3)
	v_cvt_pk_bf16_f32 v10, v10, v11
	s_waitcnt lgkmcnt(2)
	v_cvt_pk_bf16_f32 v11, v12, v13
	s_waitcnt lgkmcnt(1)
	v_cvt_pk_bf16_f32 v12, v14, v15
	s_waitcnt lgkmcnt(0)
	v_cvt_pk_bf16_f32 v13, v16, v17
	v_lshl_add_u64 v[6:7], v[6:7], 0, v[8:9]
	global_store_dwordx4 v[6:7], v[10:13], off sc1

.LBB0_30:
	s_cmpk_gt_i32 s0, 0x201f
	s_mov_b64 s[10:11], -1
	s_cbranch_scc0 .LBB0_32
	s_add_i32 s10, s1, 0xfffbfc00
	s_add_i32 s4, s0, 0xffffdfe0
	s_and_b32 s10, s10, 0x7e0
	s_andn2_b32 s4, s4, 63
	v_or_b32_e32 v0, s10, v18
	v_or_b32_e32 v6, s4, v19
	v_lshlrev_b32_e32 v0, 2, v0
	v_lshl_add_u64 v[8:9], s[42:43], 0, v[0:1]
	v_or_b32_e32 v0, 2, v6
	v_lshlrev_b64 v[12:13], 13, v[0:1]
	v_or_b32_e32 v0, 4, v6
	v_lshlrev_b64 v[14:15], 13, v[0:1]
	v_or_b32_e32 v0, 6, v6
	v_lshlrev_b64 v[16:17], 13, v[0:1]
	v_or_b32_e32 v0, 8, v6
	v_lshlrev_b64 v[34:35], 13, v[0:1]
	v_or_b32_e32 v0, 10, v6
	v_mov_b32_e32 v7, v1
	v_lshlrev_b64 v[36:37], 13, v[0:1]
	v_or_b32_e32 v0, 12, v6
	v_lshlrev_b64 v[10:11], 13, v[6:7]
	v_lshlrev_b64 v[38:39], 13, v[0:1]
	v_or_b32_e32 v0, 14, v6
	v_lshl_add_u64 v[10:11], v[8:9], 0, v[10:11]
	v_lshlrev_b64 v[40:41], 13, v[0:1]
	v_or_b32_e32 v0, 16, v6
	v_lshl_add_u64 v[12:13], v[8:9], 0, v[12:13]
	v_lshl_add_u64 v[14:15], v[8:9], 0, v[14:15]
	v_lshl_add_u64 v[16:17], v[8:9], 0, v[16:17]
	v_lshl_add_u64 v[34:35], v[8:9], 0, v[34:35]
	v_lshl_add_u64 v[36:37], v[8:9], 0, v[36:37]
	v_lshl_add_u64 v[38:39], v[8:9], 0, v[38:39]
	v_lshl_add_u64 v[40:41], v[8:9], 0, v[40:41]
	global_load_dword v33, v[10:11], off nt
	global_load_dword v42, v[12:13], off nt
	global_load_dword v43, v[14:15], off nt
	global_load_dword v44, v[16:17], off nt
	global_load_dword v45, v[34:35], off nt
	global_load_dword v46, v[36:37], off nt
	global_load_dword v47, v[38:39], off nt
	global_load_dword v48, v[40:41], off nt
	v_lshlrev_b64 v[10:11], 13, v[0:1]
	v_or_b32_e32 v0, 18, v6
	v_lshlrev_b64 v[12:13], 13, v[0:1]
	v_or_b32_e32 v0, 20, v6
	v_lshlrev_b64 v[14:15], 13, v[0:1]
	v_or_b32_e32 v0, 22, v6
	v_lshlrev_b64 v[16:17], 13, v[0:1]
	v_or_b32_e32 v0, 24, v6
	v_lshlrev_b64 v[34:35], 13, v[0:1]
	v_or_b32_e32 v0, 26, v6
	v_lshlrev_b64 v[36:37], 13, v[0:1]
	v_or_b32_e32 v0, 28, v6
	v_lshlrev_b64 v[38:39], 13, v[0:1]
	v_or_b32_e32 v0, 30, v6
	v_lshl_add_u64 v[10:11], v[8:9], 0, v[10:11]
	v_lshlrev_b64 v[40:41], 13, v[0:1]
	v_or_b32_e32 v0, 32, v6
	v_lshl_add_u64 v[12:13], v[8:9], 0, v[12:13]
	v_lshl_add_u64 v[14:15], v[8:9], 0, v[14:15]
	v_lshl_add_u64 v[16:17], v[8:9], 0, v[16:17]
	v_lshl_add_u64 v[34:35], v[8:9], 0, v[34:35]
	v_lshl_add_u64 v[36:37], v[8:9], 0, v[36:37]
	v_lshl_add_u64 v[38:39], v[8:9], 0, v[38:39]
	v_lshl_add_u64 v[40:41], v[8:9], 0, v[40:41]
	global_load_dword v49, v[10:11], off nt
	global_load_dword v50, v[12:13], off nt
	global_load_dword v51, v[14:15], off nt
	global_load_dword v52, v[16:17], off nt
	global_load_dword v53, v[34:35], off nt
	global_load_dword v54, v[36:37], off nt
	global_load_dword v55, v[38:39], off nt
	global_load_dword v56, v[40:41], off nt
	v_lshlrev_b64 v[10:11], 13, v[0:1]
	v_or_b32_e32 v0, 34, v6
	v_lshlrev_b64 v[12:13], 13, v[0:1]
	v_or_b32_e32 v0, 36, v6
	v_lshlrev_b64 v[14:15], 13, v[0:1]
	v_or_b32_e32 v0, 38, v6
	v_lshlrev_b64 v[16:17], 13, v[0:1]
	v_or_b32_e32 v0, 40, v6
	v_lshlrev_b64 v[34:35], 13, v[0:1]
	v_or_b32_e32 v0, 42, v6
	v_lshlrev_b64 v[36:37], 13, v[0:1]
	v_or_b32_e32 v0, 44, v6
	v_lshlrev_b64 v[38:39], 13, v[0:1]
	v_or_b32_e32 v0, 46, v6
	v_lshl_add_u64 v[10:11], v[8:9], 0, v[10:11]
	v_lshlrev_b64 v[40:41], 13, v[0:1]
	v_or_b32_e32 v0, 48, v6
	v_lshl_add_u64 v[12:13], v[8:9], 0, v[12:13]
	v_lshl_add_u64 v[14:15], v[8:9], 0, v[14:15]
	v_lshl_add_u64 v[16:17], v[8:9], 0, v[16:17]
	v_lshl_add_u64 v[34:35], v[8:9], 0, v[34:35]
	v_lshl_add_u64 v[36:37], v[8:9], 0, v[36:37]
	v_lshl_add_u64 v[38:39], v[8:9], 0, v[38:39]
	v_lshl_add_u64 v[40:41], v[8:9], 0, v[40:41]
	global_load_dword v57, v[10:11], off nt
	global_load_dword v58, v[12:13], off nt
	global_load_dword v59, v[14:15], off nt
	global_load_dword v60, v[16:17], off nt
	global_load_dword v61, v[34:35], off nt
	global_load_dword v62, v[36:37], off nt
	global_load_dword v63, v[38:39], off nt
	global_load_dword v64, v[40:41], off nt
	v_lshlrev_b64 v[10:11], 13, v[0:1]
	v_or_b32_e32 v0, 50, v6
	v_lshlrev_b64 v[12:13], 13, v[0:1]
	v_or_b32_e32 v0, 52, v6
	v_lshlrev_b64 v[14:15], 13, v[0:1]
	v_or_b32_e32 v0, 54, v6
	v_lshlrev_b64 v[16:17], 13, v[0:1]
	v_or_b32_e32 v0, 56, v6
	v_lshlrev_b64 v[34:35], 13, v[0:1]
	v_or_b32_e32 v0, 58, v6
	v_lshlrev_b64 v[36:37], 13, v[0:1]
	v_or_b32_e32 v0, 60, v6
	v_lshlrev_b64 v[38:39], 13, v[0:1]
	v_or_b32_e32 v0, 62, v6
	v_lshl_add_u64 v[10:11], v[8:9], 0, v[10:11]
	v_lshlrev_b64 v[6:7], 13, v[0:1]
	v_lshl_add_u64 v[12:13], v[8:9], 0, v[12:13]
	v_lshl_add_u64 v[14:15], v[8:9], 0, v[14:15]
	v_lshl_add_u64 v[16:17], v[8:9], 0, v[16:17]
	v_lshl_add_u64 v[34:35], v[8:9], 0, v[34:35]
	v_lshl_add_u64 v[36:37], v[8:9], 0, v[36:37]
	v_lshl_add_u64 v[38:39], v[8:9], 0, v[38:39]
	v_lshl_add_u64 v[6:7], v[8:9], 0, v[6:7]
	global_load_dword v0, v[10:11], off nt
	global_load_dword v8, v[12:13], off nt
	global_load_dword v9, v[14:15], off nt
	global_load_dword v40, v[16:17], off nt
	global_load_dword v41, v[34:35], off nt
	global_load_dword v65, v[36:37], off nt
	global_load_dword v66, v[38:39], off nt
	global_load_dword v67, v[6:7], off nt
	v_lshl_add_u64 v[10:11], s[4:5], 1, v[2:3]
	s_waitcnt vmcnt(30)
	ds_write2_b32 v25, v33, v42 offset1:66
	s_waitcnt vmcnt(28)
	ds_write2_b32 v25, v43, v44 offset0:132 offset1:198
	s_waitcnt vmcnt(26)
	ds_write2_b32 v26, v45, v46 offset0:8 offset1:74
	s_waitcnt vmcnt(24)
	ds_write2_b32 v26, v47, v48 offset0:140 offset1:206
	s_waitcnt vmcnt(22)
	ds_write2_b32 v27, v49, v50 offset0:16 offset1:82
	s_waitcnt vmcnt(20)
	ds_write2_b32 v27, v51, v52 offset0:148 offset1:214
	s_waitcnt vmcnt(18)
	ds_write2_b32 v28, v53, v54 offset0:24 offset1:90
	s_waitcnt vmcnt(16)
	ds_write2_b32 v28, v55, v56 offset0:156 offset1:222
	s_waitcnt vmcnt(14)
	ds_write2_b32 v29, v57, v58 offset0:32 offset1:98
	s_waitcnt vmcnt(12)
	ds_write2_b32 v29, v59, v60 offset0:164 offset1:230
	s_waitcnt vmcnt(10)
	ds_write2_b32 v30, v61, v62 offset0:40 offset1:106
	s_waitcnt vmcnt(8)
	ds_write2_b32 v30, v63, v64 offset0:172 offset1:238
	s_waitcnt vmcnt(6)
	ds_write2_b32 v31, v0, v8 offset0:48 offset1:114
	s_waitcnt vmcnt(4)
	ds_write2_b32 v31, v9, v40 offset0:180 offset1:246
	s_waitcnt vmcnt(2)
	ds_write2_b32 v32, v41, v65 offset0:56 offset1:122
	s_waitcnt vmcnt(0)
	ds_write2_b32 v32, v66, v67 offset0:188 offset1:254
	ds_read2_b32 v[12:13], v21 offset0:33 offset1:41
	ds_read2_b32 v[14:15], v21 offset1:8
	ds_read2_b32 v[16:17], v21 offset0:66 offset1:74
	ds_read2_b32 v[34:35], v21 offset0:99 offset1:107
	ds_read2_b32 v[36:37], v21 offset0:132 offset1:140
	ds_read2_b32 v[38:39], v21 offset0:165 offset1:173
	ds_read2_b32 v[40:41], v21 offset0:198 offset1:206
	ds_read2_b32 v[42:43], v21 offset0:231 offset1:239
	v_or_b32_e32 v0, s10, v20
	v_lshlrev_b32_e32 v0, 12, v0
	v_lshl_add_u64 v[44:45], v[10:11], 0, v[0:1]
	v_or_b32_e32 v0, s10, v22
	s_waitcnt lgkmcnt(6)
	v_cvt_pk_bf16_f32 v6, v14, v12
	s_waitcnt lgkmcnt(4)
	v_cvt_pk_bf16_f32 v7, v16, v34
	s_waitcnt lgkmcnt(2)
	v_cvt_pk_bf16_f32 v8, v36, v38
	s_waitcnt lgkmcnt(0)
	v_cvt_pk_bf16_f32 v9, v40, v42
	v_lshlrev_b32_e32 v0, 12, v0
	global_store_dwordx4 v[44:45], v[6:9], off sc1
	v_lshl_add_u64 v[44:45], v[10:11], 0, v[0:1]
	v_or_b32_e32 v0, s10, v23
	v_cvt_pk_bf16_f32 v6, v15, v13
	v_cvt_pk_bf16_f32 v7, v17, v35
	v_cvt_pk_bf16_f32 v8, v37, v39
	v_cvt_pk_bf16_f32 v9, v41, v43
	global_store_dwordx4 v[44:45], v[6:9], off sc1
	ds_read2_b32 v[12:13], v21 offset0:49 offset1:57
	ds_read2_b32 v[14:15], v21 offset0:16 offset1:24
	ds_read2_b32 v[16:17], v21 offset0:82 offset1:90
	ds_read2_b32 v[34:35], v21 offset0:115 offset1:123
	ds_read2_b32 v[36:37], v21 offset0:148 offset1:156
	ds_read2_b32 v[38:39], v21 offset0:181 offset1:189
	ds_read2_b32 v[40:41], v21 offset0:214 offset1:222
	ds_read2_b32 v[42:43], v21 offset0:247 offset1:255
	v_lshlrev_b32_e32 v0, 12, v0
	v_lshl_add_u64 v[44:45], v[10:11], 0, v[0:1]
	v_or_b32_e32 v0, s10, v24
	s_waitcnt lgkmcnt(6)
	v_cvt_pk_bf16_f32 v6, v14, v12
	s_waitcnt lgkmcnt(4)
	v_cvt_pk_bf16_f32 v7, v16, v34
	s_waitcnt lgkmcnt(2)
	v_cvt_pk_bf16_f32 v8, v36, v38
	s_waitcnt lgkmcnt(0)
	v_cvt_pk_bf16_f32 v9, v40, v42
	v_lshlrev_b32_e32 v0, 12, v0
	global_store_dwordx4 v[44:45], v[6:9], off sc1
	v_lshl_add_u64 v[10:11], v[10:11], 0, v[0:1]
	s_nop 0
	v_cvt_pk_bf16_f32 v6, v15, v13
	v_cvt_pk_bf16_f32 v7, v17, v35
	v_cvt_pk_bf16_f32 v8, v37, v39
	v_cvt_pk_bf16_f32 v9, v41, v43
	global_store_dwordx4 v[10:11], v[6:9], off sc1
	s_cbranch_execnz .LBB0_29
	s_branch .LBB0_33

.LBB0_103:
	s_or_b64 exec, exec, s[12:13]
	v_ashrrev_i32_e32 v9, 31, v8
	v_lshlrev_b64 v[8:9], 12, v[8:9]
	s_waitcnt lgkmcnt(3)
	v_cvt_pk_bf16_f32 v10, v10, v11
	s_waitcnt lgkmcnt(2)
	v_cvt_pk_bf16_f32 v11, v12, v13
	s_waitcnt lgkmcnt(1)
	v_cvt_pk_bf16_f32 v12, v14, v15
	s_waitcnt lgkmcnt(0)
	v_cvt_pk_bf16_f32 v13, v16, v17
	v_lshl_add_u64 v[8:9], v[6:7], 0, v[8:9]
	global_store_dwordx4 v[8:9], v[10:13], off sc1

.LBB0_198:
	v_ashrrev_i32_e32 v147, 31, v146
	v_lshl_or_b32 v148, s74, 8, v155
	v_lshlrev_b64 v[150:151], 14, v[146:147]
	v_ashrrev_i32_e32 v149, 31, v148
	v_lshl_add_u64 v[150:151], s[10:11], 0, v[150:151]
	v_lshl_add_u64 v[150:151], v[148:149], 1, v[150:151]
	v_cvt_pk_bf16_f32 v124, v124, v125
	v_cvt_pk_bf16_f32 v125, v126, v127
	v_cvt_pk_bf16_f32 v126, v120, v121
	v_cvt_pk_bf16_f32 v127, v122, v123
	s_and_b64 vcc, exec, s[4:5]
	global_store_dwordx4 v[150:151], v[124:127], off nt
	s_cbranch_vccnz .LBB0_200
	v_mul_f32_e32 v121, 0xbfb8aa3b, v112
	v_mul_f32_e32 v122, 0xbfb8aa3b, v117
	v_exp_f32_e32 v121, v121
	v_exp_f32_e32 v123, v122
	v_mul_f32_e32 v125, 0xbfb8aa3b, v114
	v_mul_f32_e32 v126, 0xbfb8aa3b, v119
	v_add_f32_e32 v121, 1.0, v121
	v_mul_f32_e32 v120, 0xbfb8aa3b, v116
	v_rcp_f32_e32 v122, v121
	v_add_f32_e32 v121, 1.0, v123
	v_mul_f32_e32 v123, 0xbfb8aa3b, v113
	v_mul_f32_e32 v124, 0xbfb8aa3b, v118
	v_exp_f32_e32 v125, v125
	v_exp_f32_e32 v127, v126
	v_mul_f32_e32 v126, 0xbfb8aa3b, v115
	v_exp_f32_e32 v120, v120
	v_exp_f32_e32 v123, v123
	v_exp_f32_e32 v124, v124
	v_exp_f32_e32 v159, v126
	v_add_f32_e32 v125, 1.0, v125
	v_add_f32_e32 v120, 1.0, v120
	v_add_f32_e32 v123, 1.0, v123
	v_add_f32_e32 v124, 1.0, v124
	v_rcp_f32_e32 v126, v125
	v_add_f32_e32 v125, 1.0, v127
	v_add_f32_e32 v127, 1.0, v159
	v_rcp_f32_e32 v120, v120
	v_rcp_f32_e32 v121, v121
	v_rcp_f32_e32 v124, v124
	v_rcp_f32_e32 v125, v125
	v_rcp_f32_e32 v127, v127
	v_rcp_f32_e32 v123, v123
	v_pk_mul_f32 v[116:117], v[116:117], v[120:121]
	v_pk_mul_f32 v[118:119], v[118:119], v[124:125]
	v_pk_mul_f32 v[114:115], v[114:115], v[126:127]
	v_pk_mul_f32 v[112:113], v[112:113], v[122:123]
.LBB0_200:
	v_cvt_pk_bf16_f32 v116, v116, v117
	v_cvt_pk_bf16_f32 v117, v118, v119
	v_cvt_pk_bf16_f32 v118, v112, v113
	v_cvt_pk_bf16_f32 v119, v114, v115
	s_and_b64 vcc, exec, s[4:5]
	global_store_dwordx4 v[150:151], v[116:119], off offset:256 nt
	s_cbranch_vccnz .LBB0_202
	v_mul_f32_e32 v113, 0xbfb8aa3b, v104
	v_mul_f32_e32 v114, 0xbfb8aa3b, v109
	v_exp_f32_e32 v113, v113
	v_exp_f32_e32 v115, v114
	v_mul_f32_e32 v117, 0xbfb8aa3b, v106
	v_mul_f32_e32 v118, 0xbfb8aa3b, v111
	v_add_f32_e32 v113, 1.0, v113
	v_mul_f32_e32 v112, 0xbfb8aa3b, v108
	v_rcp_f32_e32 v114, v113
	v_add_f32_e32 v113, 1.0, v115
	v_mul_f32_e32 v115, 0xbfb8aa3b, v105
	v_mul_f32_e32 v116, 0xbfb8aa3b, v110
	v_exp_f32_e32 v117, v117
	v_exp_f32_e32 v119, v118
	v_mul_f32_e32 v118, 0xbfb8aa3b, v107
	v_exp_f32_e32 v112, v112
	v_exp_f32_e32 v115, v115
	v_exp_f32_e32 v116, v116
	v_exp_f32_e32 v120, v118
	v_add_f32_e32 v117, 1.0, v117
	v_add_f32_e32 v112, 1.0, v112
	v_add_f32_e32 v115, 1.0, v115
	v_add_f32_e32 v116, 1.0, v116
	v_rcp_f32_e32 v118, v117
	v_add_f32_e32 v117, 1.0, v119
	v_add_f32_e32 v119, 1.0, v120
	v_rcp_f32_e32 v112, v112
	v_rcp_f32_e32 v113, v113
	v_rcp_f32_e32 v116, v116
	v_rcp_f32_e32 v117, v117
	v_rcp_f32_e32 v119, v119
	v_rcp_f32_e32 v115, v115
	v_pk_mul_f32 v[108:109], v[108:109], v[112:113]
	v_pk_mul_f32 v[110:111], v[110:111], v[116:117]
	v_pk_mul_f32 v[106:107], v[106:107], v[118:119]
	v_pk_mul_f32 v[104:105], v[104:105], v[114:115]
.LBB0_202:
	v_or_b32_e32 v112, 16, v146
	v_ashrrev_i32_e32 v113, 31, v112
	v_lshlrev_b64 v[112:113], 14, v[112:113]
	v_lshl_add_u64 v[112:113], s[10:11], 0, v[112:113]
	v_lshl_add_u64 v[112:113], v[148:149], 1, v[112:113]
	v_cvt_pk_bf16_f32 v108, v108, v109
	v_cvt_pk_bf16_f32 v109, v110, v111
	v_cvt_pk_bf16_f32 v110, v104, v105
	v_cvt_pk_bf16_f32 v111, v106, v107
	s_and_b64 vcc, exec, s[4:5]
	global_store_dwordx4 v[112:113], v[108:111], off nt
	s_cbranch_vccnz .LBB0_204
	v_mul_f32_e32 v105, 0xbfb8aa3b, v96
	v_mul_f32_e32 v106, 0xbfb8aa3b, v101
	v_exp_f32_e32 v105, v105
	v_exp_f32_e32 v107, v106
	v_mul_f32_e32 v109, 0xbfb8aa3b, v98
	v_mul_f32_e32 v110, 0xbfb8aa3b, v103
	v_add_f32_e32 v105, 1.0, v105
	v_mul_f32_e32 v104, 0xbfb8aa3b, v100
	v_rcp_f32_e32 v106, v105
	v_add_f32_e32 v105, 1.0, v107
	v_mul_f32_e32 v107, 0xbfb8aa3b, v97
	v_mul_f32_e32 v108, 0xbfb8aa3b, v102
	v_exp_f32_e32 v109, v109
	v_exp_f32_e32 v111, v110
	v_mul_f32_e32 v110, 0xbfb8aa3b, v99
	v_exp_f32_e32 v104, v104
	v_exp_f32_e32 v107, v107
	v_exp_f32_e32 v108, v108
	v_exp_f32_e32 v114, v110
	v_add_f32_e32 v109, 1.0, v109
	v_add_f32_e32 v104, 1.0, v104
	v_add_f32_e32 v107, 1.0, v107
	v_add_f32_e32 v108, 1.0, v108
	v_rcp_f32_e32 v110, v109
	v_add_f32_e32 v109, 1.0, v111
	v_add_f32_e32 v111, 1.0, v114
	v_rcp_f32_e32 v104, v104
	v_rcp_f32_e32 v105, v105
	v_rcp_f32_e32 v108, v108
	v_rcp_f32_e32 v109, v109
	v_rcp_f32_e32 v111, v111
	v_rcp_f32_e32 v107, v107
	v_pk_mul_f32 v[100:101], v[100:101], v[104:105]
	v_pk_mul_f32 v[102:103], v[102:103], v[108:109]
	v_pk_mul_f32 v[98:99], v[98:99], v[110:111]
	v_pk_mul_f32 v[96:97], v[96:97], v[106:107]
.LBB0_204:
	v_cvt_pk_bf16_f32 v100, v100, v101
	v_cvt_pk_bf16_f32 v101, v102, v103
	v_cvt_pk_bf16_f32 v102, v96, v97
	v_cvt_pk_bf16_f32 v103, v98, v99
	s_and_b64 vcc, exec, s[4:5]
	global_store_dwordx4 v[112:113], v[100:103], off offset:256 nt
	s_cbranch_vccnz .LBB0_206
	v_mul_f32_e32 v97, 0xbfb8aa3b, v88
	v_mul_f32_e32 v98, 0xbfb8aa3b, v93
	v_exp_f32_e32 v97, v97
	v_exp_f32_e32 v99, v98
	v_mul_f32_e32 v101, 0xbfb8aa3b, v90
	v_mul_f32_e32 v102, 0xbfb8aa3b, v95
	v_add_f32_e32 v97, 1.0, v97
	v_mul_f32_e32 v96, 0xbfb8aa3b, v92
	v_rcp_f32_e32 v98, v97
	v_add_f32_e32 v97, 1.0, v99
	v_mul_f32_e32 v99, 0xbfb8aa3b, v89
	v_mul_f32_e32 v100, 0xbfb8aa3b, v94
	v_exp_f32_e32 v101, v101
	v_exp_f32_e32 v103, v102
	v_mul_f32_e32 v102, 0xbfb8aa3b, v91
	v_exp_f32_e32 v96, v96
	v_exp_f32_e32 v99, v99
	v_exp_f32_e32 v100, v100
	v_exp_f32_e32 v104, v102
	v_add_f32_e32 v101, 1.0, v101
	v_add_f32_e32 v96, 1.0, v96
	v_add_f32_e32 v99, 1.0, v99
	v_add_f32_e32 v100, 1.0, v100
	v_rcp_f32_e32 v102, v101
	v_add_f32_e32 v101, 1.0, v103
	v_add_f32_e32 v103, 1.0, v104
	v_rcp_f32_e32 v96, v96
	v_rcp_f32_e32 v97, v97
	v_rcp_f32_e32 v100, v100
	v_rcp_f32_e32 v101, v101
	v_rcp_f32_e32 v103, v103
	v_rcp_f32_e32 v99, v99
	v_pk_mul_f32 v[92:93], v[92:93], v[96:97]
	v_pk_mul_f32 v[94:95], v[94:95], v[100:101]
	v_pk_mul_f32 v[90:91], v[90:91], v[102:103]
	v_pk_mul_f32 v[88:89], v[88:89], v[98:99]
.LBB0_206:
	v_or_b32_e32 v96, 32, v146
	v_ashrrev_i32_e32 v97, 31, v96
	v_lshlrev_b64 v[96:97], 14, v[96:97]
	v_lshl_add_u64 v[96:97], s[10:11], 0, v[96:97]
	v_lshl_add_u64 v[96:97], v[148:149], 1, v[96:97]
	v_cvt_pk_bf16_f32 v92, v92, v93
	v_cvt_pk_bf16_f32 v93, v94, v95
	v_cvt_pk_bf16_f32 v94, v88, v89
	v_cvt_pk_bf16_f32 v95, v90, v91
	s_and_b64 vcc, exec, s[4:5]
	global_store_dwordx4 v[96:97], v[92:95], off nt
	s_cbranch_vccnz .LBB0_208
	v_mul_f32_e32 v89, 0xbfb8aa3b, v80
	v_mul_f32_e32 v90, 0xbfb8aa3b, v85
	v_exp_f32_e32 v89, v89
	v_exp_f32_e32 v91, v90
	v_mul_f32_e32 v93, 0xbfb8aa3b, v82
	v_mul_f32_e32 v94, 0xbfb8aa3b, v87
	v_add_f32_e32 v89, 1.0, v89
	v_mul_f32_e32 v88, 0xbfb8aa3b, v84
	v_rcp_f32_e32 v90, v89
	v_add_f32_e32 v89, 1.0, v91
	v_mul_f32_e32 v91, 0xbfb8aa3b, v81
	v_mul_f32_e32 v92, 0xbfb8aa3b, v86
	v_exp_f32_e32 v93, v93
	v_exp_f32_e32 v95, v94
	v_mul_f32_e32 v94, 0xbfb8aa3b, v83
	v_exp_f32_e32 v88, v88
	v_exp_f32_e32 v91, v91
	v_exp_f32_e32 v92, v92
	v_exp_f32_e32 v98, v94
	v_add_f32_e32 v93, 1.0, v93
	v_add_f32_e32 v88, 1.0, v88
	v_add_f32_e32 v91, 1.0, v91
	v_add_f32_e32 v92, 1.0, v92
	v_rcp_f32_e32 v94, v93
	v_add_f32_e32 v93, 1.0, v95
	v_add_f32_e32 v95, 1.0, v98
	v_rcp_f32_e32 v88, v88
	v_rcp_f32_e32 v89, v89
	v_rcp_f32_e32 v92, v92
	v_rcp_f32_e32 v93, v93
	v_rcp_f32_e32 v95, v95
	v_rcp_f32_e32 v91, v91
	v_pk_mul_f32 v[84:85], v[84:85], v[88:89]
	v_pk_mul_f32 v[86:87], v[86:87], v[92:93]
	v_pk_mul_f32 v[82:83], v[82:83], v[94:95]
	v_pk_mul_f32 v[80:81], v[80:81], v[90:91]
.LBB0_208:
	v_cvt_pk_bf16_f32 v84, v84, v85
	v_cvt_pk_bf16_f32 v85, v86, v87
	v_cvt_pk_bf16_f32 v86, v80, v81
	v_cvt_pk_bf16_f32 v87, v82, v83
	s_and_b64 vcc, exec, s[4:5]
	global_store_dwordx4 v[96:97], v[84:87], off offset:256 nt
	s_cbranch_vccnz .LBB0_210
	v_mul_f32_e32 v81, 0xbfb8aa3b, v72
	v_mul_f32_e32 v82, 0xbfb8aa3b, v77
	v_exp_f32_e32 v81, v81
	v_exp_f32_e32 v83, v82
	v_mul_f32_e32 v85, 0xbfb8aa3b, v74
	v_mul_f32_e32 v86, 0xbfb8aa3b, v79
	v_add_f32_e32 v81, 1.0, v81
	v_mul_f32_e32 v80, 0xbfb8aa3b, v76
	v_rcp_f32_e32 v82, v81
	v_add_f32_e32 v81, 1.0, v83
	v_mul_f32_e32 v83, 0xbfb8aa3b, v73
	v_mul_f32_e32 v84, 0xbfb8aa3b, v78
	v_exp_f32_e32 v85, v85
	v_exp_f32_e32 v87, v86
	v_mul_f32_e32 v86, 0xbfb8aa3b, v75
	v_exp_f32_e32 v80, v80
	v_exp_f32_e32 v83, v83
	v_exp_f32_e32 v84, v84
	v_exp_f32_e32 v88, v86
	v_add_f32_e32 v85, 1.0, v85
	v_add_f32_e32 v80, 1.0, v80
	v_add_f32_e32 v83, 1.0, v83
	v_add_f32_e32 v84, 1.0, v84
	v_rcp_f32_e32 v86, v85
	v_add_f32_e32 v85, 1.0, v87
	v_add_f32_e32 v87, 1.0, v88
	v_rcp_f32_e32 v80, v80
	v_rcp_f32_e32 v81, v81
	v_rcp_f32_e32 v84, v84
	v_rcp_f32_e32 v85, v85
	v_rcp_f32_e32 v87, v87
	v_rcp_f32_e32 v83, v83
	v_pk_mul_f32 v[76:77], v[76:77], v[80:81]
	v_pk_mul_f32 v[78:79], v[78:79], v[84:85]
	v_pk_mul_f32 v[74:75], v[74:75], v[86:87]
	v_pk_mul_f32 v[72:73], v[72:73], v[82:83]
.LBB0_210:
	v_or_b32_e32 v80, 48, v146
	v_ashrrev_i32_e32 v81, 31, v80
	v_lshlrev_b64 v[80:81], 14, v[80:81]
	v_lshl_add_u64 v[80:81], s[10:11], 0, v[80:81]
	v_lshl_add_u64 v[80:81], v[148:149], 1, v[80:81]
	v_cvt_pk_bf16_f32 v76, v76, v77
	v_cvt_pk_bf16_f32 v77, v78, v79
	v_cvt_pk_bf16_f32 v78, v72, v73
	v_cvt_pk_bf16_f32 v79, v74, v75
	s_and_b64 vcc, exec, s[4:5]
	global_store_dwordx4 v[80:81], v[76:79], off nt
	s_cbranch_vccnz .LBB0_212
	v_mul_f32_e32 v73, 0xbfb8aa3b, v64
	v_mul_f32_e32 v74, 0xbfb8aa3b, v69
	v_exp_f32_e32 v73, v73
	v_exp_f32_e32 v75, v74
	v_mul_f32_e32 v77, 0xbfb8aa3b, v66
	v_mul_f32_e32 v78, 0xbfb8aa3b, v71
	v_add_f32_e32 v73, 1.0, v73
	v_mul_f32_e32 v72, 0xbfb8aa3b, v68
	v_rcp_f32_e32 v74, v73
	v_add_f32_e32 v73, 1.0, v75
	v_mul_f32_e32 v75, 0xbfb8aa3b, v65
	v_mul_f32_e32 v76, 0xbfb8aa3b, v70
	v_exp_f32_e32 v77, v77
	v_exp_f32_e32 v79, v78
	v_mul_f32_e32 v78, 0xbfb8aa3b, v67
	v_exp_f32_e32 v72, v72
	v_exp_f32_e32 v75, v75
	v_exp_f32_e32 v76, v76
	v_exp_f32_e32 v82, v78
	v_add_f32_e32 v77, 1.0, v77
	v_add_f32_e32 v72, 1.0, v72
	v_add_f32_e32 v75, 1.0, v75
	v_add_f32_e32 v76, 1.0, v76
	v_rcp_f32_e32 v78, v77
	v_add_f32_e32 v77, 1.0, v79
	v_add_f32_e32 v79, 1.0, v82
	v_rcp_f32_e32 v72, v72
	v_rcp_f32_e32 v73, v73
	v_rcp_f32_e32 v76, v76
	v_rcp_f32_e32 v77, v77
	v_rcp_f32_e32 v79, v79
	v_rcp_f32_e32 v75, v75
	v_pk_mul_f32 v[68:69], v[68:69], v[72:73]
	v_pk_mul_f32 v[70:71], v[70:71], v[76:77]
	v_pk_mul_f32 v[66:67], v[66:67], v[78:79]
	v_pk_mul_f32 v[64:65], v[64:65], v[74:75]
.LBB0_212:
	v_cvt_pk_bf16_f32 v68, v68, v69
	v_cvt_pk_bf16_f32 v69, v70, v71
	v_cvt_pk_bf16_f32 v70, v64, v65
	v_cvt_pk_bf16_f32 v71, v66, v67
	s_and_b64 vcc, exec, s[4:5]
	global_store_dwordx4 v[80:81], v[68:71], off offset:256 nt
	s_cbranch_vccnz .LBB0_214
	v_mul_f32_e32 v65, 0xbfb8aa3b, v56
	v_mul_f32_e32 v66, 0xbfb8aa3b, v61
	v_exp_f32_e32 v65, v65
	v_exp_f32_e32 v67, v66
	v_mul_f32_e32 v69, 0xbfb8aa3b, v58
	v_mul_f32_e32 v70, 0xbfb8aa3b, v63
	v_add_f32_e32 v65, 1.0, v65
	v_mul_f32_e32 v64, 0xbfb8aa3b, v60
	v_rcp_f32_e32 v66, v65
	v_add_f32_e32 v65, 1.0, v67
	v_mul_f32_e32 v67, 0xbfb8aa3b, v57
	v_mul_f32_e32 v68, 0xbfb8aa3b, v62
	v_exp_f32_e32 v69, v69
	v_exp_f32_e32 v71, v70
	v_mul_f32_e32 v70, 0xbfb8aa3b, v59
	v_exp_f32_e32 v64, v64
	v_exp_f32_e32 v67, v67
	v_exp_f32_e32 v68, v68
	v_exp_f32_e32 v72, v70
	v_add_f32_e32 v69, 1.0, v69
	v_add_f32_e32 v64, 1.0, v64
	v_add_f32_e32 v67, 1.0, v67
	v_add_f32_e32 v68, 1.0, v68
	v_rcp_f32_e32 v70, v69
	v_add_f32_e32 v69, 1.0, v71
	v_add_f32_e32 v71, 1.0, v72
	v_rcp_f32_e32 v64, v64
	v_rcp_f32_e32 v65, v65
	v_rcp_f32_e32 v68, v68
	v_rcp_f32_e32 v69, v69
	v_rcp_f32_e32 v71, v71
	v_rcp_f32_e32 v67, v67
	v_pk_mul_f32 v[60:61], v[60:61], v[64:65]
	v_pk_mul_f32 v[62:63], v[62:63], v[68:69]
	v_pk_mul_f32 v[58:59], v[58:59], v[70:71]
	v_pk_mul_f32 v[56:57], v[56:57], v[66:67]
.LBB0_214:
	v_lshlrev_b64 v[64:65], 14, v[146:147]
	v_lshl_add_u64 v[64:65], s[10:11], 0, v[64:65]
	v_lshl_add_u64 v[64:65], v[148:149], 1, v[64:65]
	v_cvt_pk_bf16_f32 v60, v60, v61
	v_cvt_pk_bf16_f32 v61, v62, v63
	v_cvt_pk_bf16_f32 v62, v56, v57
	v_add_co_u32_e32 v56, vcc, 0x200000, v64
	v_cvt_pk_bf16_f32 v63, v58, v59
	s_nop 0
	v_addc_co_u32_e32 v57, vcc, 0, v65, vcc
	s_and_b64 vcc, exec, s[4:5]
	global_store_dwordx4 v[56:57], v[60:63], off nt
	s_cbranch_vccnz .LBB0_216
	v_mul_f32_e32 v57, 0xbfb8aa3b, v48
	v_mul_f32_e32 v58, 0xbfb8aa3b, v53
	v_exp_f32_e32 v57, v57
	v_exp_f32_e32 v59, v58
	v_mul_f32_e32 v61, 0xbfb8aa3b, v50
	v_mul_f32_e32 v62, 0xbfb8aa3b, v55
	v_add_f32_e32 v57, 1.0, v57
	v_mul_f32_e32 v56, 0xbfb8aa3b, v52
	v_rcp_f32_e32 v58, v57
	v_add_f32_e32 v57, 1.0, v59
	v_mul_f32_e32 v59, 0xbfb8aa3b, v49
	v_mul_f32_e32 v60, 0xbfb8aa3b, v54
	v_exp_f32_e32 v61, v61
	v_exp_f32_e32 v63, v62
	v_mul_f32_e32 v62, 0xbfb8aa3b, v51
	v_exp_f32_e32 v56, v56
	v_exp_f32_e32 v59, v59
	v_exp_f32_e32 v60, v60
	v_exp_f32_e32 v66, v62
	v_add_f32_e32 v61, 1.0, v61
	v_add_f32_e32 v56, 1.0, v56
	v_add_f32_e32 v59, 1.0, v59
	v_add_f32_e32 v60, 1.0, v60
	v_rcp_f32_e32 v62, v61
	v_add_f32_e32 v61, 1.0, v63
	v_add_f32_e32 v63, 1.0, v66
	v_rcp_f32_e32 v56, v56
	v_rcp_f32_e32 v57, v57
	v_rcp_f32_e32 v60, v60
	v_rcp_f32_e32 v61, v61
	v_rcp_f32_e32 v63, v63
	v_rcp_f32_e32 v59, v59
	v_pk_mul_f32 v[52:53], v[52:53], v[56:57]
	v_pk_mul_f32 v[54:55], v[54:55], v[60:61]
	v_pk_mul_f32 v[50:51], v[50:51], v[62:63]
	v_pk_mul_f32 v[48:49], v[48:49], v[58:59]
.LBB0_216:
	v_lshl_add_u64 v[56:57], v[64:65], 0, s[58:59]
	v_cvt_pk_bf16_f32 v52, v52, v53
	v_cvt_pk_bf16_f32 v53, v54, v55
	v_cvt_pk_bf16_f32 v54, v48, v49
	v_cvt_pk_bf16_f32 v55, v50, v51
	s_and_b64 vcc, exec, s[4:5]
	global_store_dwordx4 v[56:57], v[52:55], off offset:256 nt
	s_cbranch_vccnz .LBB0_218
	v_mul_f32_e32 v49, 0xbfb8aa3b, v40
	v_mul_f32_e32 v50, 0xbfb8aa3b, v45
	v_exp_f32_e32 v49, v49
	v_exp_f32_e32 v51, v50
	v_mul_f32_e32 v53, 0xbfb8aa3b, v42
	v_mul_f32_e32 v54, 0xbfb8aa3b, v47
	v_add_f32_e32 v49, 1.0, v49
	v_mul_f32_e32 v48, 0xbfb8aa3b, v44
	v_rcp_f32_e32 v50, v49
	v_add_f32_e32 v49, 1.0, v51
	v_mul_f32_e32 v51, 0xbfb8aa3b, v41
	v_mul_f32_e32 v52, 0xbfb8aa3b, v46
	v_exp_f32_e32 v53, v53
	v_exp_f32_e32 v55, v54
	v_mul_f32_e32 v54, 0xbfb8aa3b, v43
	v_exp_f32_e32 v48, v48
	v_exp_f32_e32 v51, v51
	v_exp_f32_e32 v52, v52
	v_exp_f32_e32 v56, v54
	v_add_f32_e32 v53, 1.0, v53
	v_add_f32_e32 v48, 1.0, v48
	v_add_f32_e32 v51, 1.0, v51
	v_add_f32_e32 v52, 1.0, v52
	v_rcp_f32_e32 v54, v53
	v_add_f32_e32 v53, 1.0, v55
	v_add_f32_e32 v55, 1.0, v56
	v_rcp_f32_e32 v48, v48
	v_rcp_f32_e32 v49, v49
	v_rcp_f32_e32 v52, v52
	v_rcp_f32_e32 v53, v53
	v_rcp_f32_e32 v55, v55
	v_rcp_f32_e32 v51, v51
	v_pk_mul_f32 v[44:45], v[44:45], v[48:49]
	v_pk_mul_f32 v[46:47], v[46:47], v[52:53]
	v_pk_mul_f32 v[42:43], v[42:43], v[54:55]
	v_pk_mul_f32 v[40:41], v[40:41], v[50:51]
.LBB0_218:
	v_lshlrev_b64 v[48:49], 14, v[146:147]
	v_lshl_add_u64 v[48:49], s[10:11], 0, v[48:49]
	v_lshl_add_u64 v[48:49], v[148:149], 1, v[48:49]
	v_cvt_pk_bf16_f32 v44, v44, v45
	v_cvt_pk_bf16_f32 v45, v46, v47
	v_cvt_pk_bf16_f32 v46, v40, v41
	v_add_co_u32_e32 v40, vcc, 0x240000, v48
	v_cvt_pk_bf16_f32 v47, v42, v43
	s_nop 0
	v_addc_co_u32_e32 v41, vcc, 0, v49, vcc
	s_and_b64 vcc, exec, s[4:5]
	global_store_dwordx4 v[40:41], v[44:47], off nt
	s_cbranch_vccnz .LBB0_220
	v_mul_f32_e32 v41, 0xbfb8aa3b, v32
	v_mul_f32_e32 v42, 0xbfb8aa3b, v37
	v_exp_f32_e32 v41, v41
	v_exp_f32_e32 v43, v42
	v_mul_f32_e32 v45, 0xbfb8aa3b, v34
	v_mul_f32_e32 v46, 0xbfb8aa3b, v39
	v_add_f32_e32 v41, 1.0, v41
	v_mul_f32_e32 v40, 0xbfb8aa3b, v36
	v_rcp_f32_e32 v42, v41
	v_add_f32_e32 v41, 1.0, v43
	v_mul_f32_e32 v43, 0xbfb8aa3b, v33
	v_mul_f32_e32 v44, 0xbfb8aa3b, v38
	v_exp_f32_e32 v45, v45
	v_exp_f32_e32 v47, v46
	v_mul_f32_e32 v46, 0xbfb8aa3b, v35
	v_exp_f32_e32 v40, v40
	v_exp_f32_e32 v43, v43
	v_exp_f32_e32 v44, v44
	v_exp_f32_e32 v50, v46
	v_add_f32_e32 v45, 1.0, v45
	v_add_f32_e32 v40, 1.0, v40
	v_add_f32_e32 v43, 1.0, v43
	v_add_f32_e32 v44, 1.0, v44
	v_rcp_f32_e32 v46, v45
	v_add_f32_e32 v45, 1.0, v47
	v_add_f32_e32 v47, 1.0, v50
	v_rcp_f32_e32 v40, v40
	v_rcp_f32_e32 v41, v41
	v_rcp_f32_e32 v44, v44
	v_rcp_f32_e32 v45, v45
	v_rcp_f32_e32 v47, v47
	v_rcp_f32_e32 v43, v43
	v_pk_mul_f32 v[36:37], v[36:37], v[40:41]
	v_pk_mul_f32 v[38:39], v[38:39], v[44:45]
	v_pk_mul_f32 v[34:35], v[34:35], v[46:47]
	v_pk_mul_f32 v[32:33], v[32:33], v[42:43]
.LBB0_220:
	v_lshl_add_u64 v[40:41], v[48:49], 0, s[60:61]
	v_cvt_pk_bf16_f32 v36, v36, v37
	v_cvt_pk_bf16_f32 v37, v38, v39
	v_cvt_pk_bf16_f32 v38, v32, v33
	v_cvt_pk_bf16_f32 v39, v34, v35
	s_and_b64 vcc, exec, s[4:5]
	global_store_dwordx4 v[40:41], v[36:39], off offset:256 nt
	s_cbranch_vccnz .LBB0_222
	v_mul_f32_e32 v33, 0xbfb8aa3b, v24
	v_mul_f32_e32 v34, 0xbfb8aa3b, v29
	v_exp_f32_e32 v33, v33
	v_exp_f32_e32 v35, v34
	v_mul_f32_e32 v37, 0xbfb8aa3b, v26
	v_mul_f32_e32 v38, 0xbfb8aa3b, v31
	v_add_f32_e32 v33, 1.0, v33
	v_mul_f32_e32 v32, 0xbfb8aa3b, v28
	v_rcp_f32_e32 v34, v33
	v_add_f32_e32 v33, 1.0, v35
	v_mul_f32_e32 v35, 0xbfb8aa3b, v25
	v_mul_f32_e32 v36, 0xbfb8aa3b, v30
	v_exp_f32_e32 v37, v37
	v_exp_f32_e32 v39, v38
	v_mul_f32_e32 v38, 0xbfb8aa3b, v27
	v_exp_f32_e32 v32, v32
	v_exp_f32_e32 v35, v35
	v_exp_f32_e32 v36, v36
	v_exp_f32_e32 v40, v38
	v_add_f32_e32 v37, 1.0, v37
	v_add_f32_e32 v32, 1.0, v32
	v_add_f32_e32 v35, 1.0, v35
	v_add_f32_e32 v36, 1.0, v36
	v_rcp_f32_e32 v38, v37
	v_add_f32_e32 v37, 1.0, v39
	v_add_f32_e32 v39, 1.0, v40
	v_rcp_f32_e32 v32, v32
	v_rcp_f32_e32 v33, v33
	v_rcp_f32_e32 v36, v36
	v_rcp_f32_e32 v37, v37
	v_rcp_f32_e32 v39, v39
	v_rcp_f32_e32 v35, v35
	v_pk_mul_f32 v[28:29], v[28:29], v[32:33]
	v_pk_mul_f32 v[30:31], v[30:31], v[36:37]
	v_pk_mul_f32 v[26:27], v[26:27], v[38:39]
	v_pk_mul_f32 v[24:25], v[24:25], v[34:35]
.LBB0_222:
	v_lshlrev_b64 v[32:33], 14, v[146:147]
	v_lshl_add_u64 v[32:33], s[10:11], 0, v[32:33]
	v_lshl_add_u64 v[32:33], v[148:149], 1, v[32:33]
	v_cvt_pk_bf16_f32 v28, v28, v29
	v_cvt_pk_bf16_f32 v29, v30, v31
	v_cvt_pk_bf16_f32 v30, v24, v25
	v_add_co_u32_e32 v24, vcc, 0x280000, v32
	v_cvt_pk_bf16_f32 v31, v26, v27
	s_nop 0
	v_addc_co_u32_e32 v25, vcc, 0, v33, vcc
	s_and_b64 vcc, exec, s[4:5]
	global_store_dwordx4 v[24:25], v[28:31], off nt
	s_cbranch_vccnz .LBB0_224
	v_mul_f32_e32 v25, 0xbfb8aa3b, v16
	v_mul_f32_e32 v26, 0xbfb8aa3b, v21
	v_exp_f32_e32 v25, v25
	v_exp_f32_e32 v27, v26
	v_mul_f32_e32 v29, 0xbfb8aa3b, v18
	v_mul_f32_e32 v30, 0xbfb8aa3b, v23
	v_add_f32_e32 v25, 1.0, v25
	v_mul_f32_e32 v24, 0xbfb8aa3b, v20
	v_rcp_f32_e32 v26, v25
	v_add_f32_e32 v25, 1.0, v27
	v_mul_f32_e32 v27, 0xbfb8aa3b, v17
	v_mul_f32_e32 v28, 0xbfb8aa3b, v22
	v_exp_f32_e32 v29, v29
	v_exp_f32_e32 v31, v30
	v_mul_f32_e32 v30, 0xbfb8aa3b, v19
	v_exp_f32_e32 v24, v24
	v_exp_f32_e32 v27, v27
	v_exp_f32_e32 v28, v28
	v_exp_f32_e32 v34, v30
	v_add_f32_e32 v29, 1.0, v29
	v_add_f32_e32 v24, 1.0, v24
	v_add_f32_e32 v27, 1.0, v27
	v_add_f32_e32 v28, 1.0, v28
	v_rcp_f32_e32 v30, v29
	v_add_f32_e32 v29, 1.0, v31
	v_add_f32_e32 v31, 1.0, v34
	v_rcp_f32_e32 v24, v24
	v_rcp_f32_e32 v25, v25
	v_rcp_f32_e32 v28, v28
	v_rcp_f32_e32 v29, v29
	v_rcp_f32_e32 v31, v31
	v_rcp_f32_e32 v27, v27
	v_pk_mul_f32 v[20:21], v[20:21], v[24:25]
	v_pk_mul_f32 v[22:23], v[22:23], v[28:29]
	v_pk_mul_f32 v[18:19], v[18:19], v[30:31]
	v_pk_mul_f32 v[16:17], v[16:17], v[26:27]
.LBB0_224:
	v_lshl_add_u64 v[24:25], v[32:33], 0, s[62:63]
	v_cvt_pk_bf16_f32 v20, v20, v21
	v_cvt_pk_bf16_f32 v21, v22, v23
	v_cvt_pk_bf16_f32 v22, v16, v17
	v_cvt_pk_bf16_f32 v23, v18, v19
	s_and_b64 vcc, exec, s[4:5]
	global_store_dwordx4 v[24:25], v[20:23], off offset:256 nt
	s_cbranch_vccnz .LBB0_226
	v_mul_f32_e32 v17, 0xbfb8aa3b, v8
	v_mul_f32_e32 v18, 0xbfb8aa3b, v13
	v_exp_f32_e32 v17, v17
	v_exp_f32_e32 v19, v18
	v_mul_f32_e32 v21, 0xbfb8aa3b, v10
	v_mul_f32_e32 v22, 0xbfb8aa3b, v15
	v_add_f32_e32 v17, 1.0, v17
	v_mul_f32_e32 v16, 0xbfb8aa3b, v12
	v_rcp_f32_e32 v18, v17
	v_add_f32_e32 v17, 1.0, v19
	v_mul_f32_e32 v19, 0xbfb8aa3b, v9
	v_mul_f32_e32 v20, 0xbfb8aa3b, v14
	v_exp_f32_e32 v21, v21
	v_exp_f32_e32 v23, v22
	v_mul_f32_e32 v22, 0xbfb8aa3b, v11
	v_exp_f32_e32 v16, v16
	v_exp_f32_e32 v19, v19
	v_exp_f32_e32 v20, v20
	v_exp_f32_e32 v24, v22
	v_add_f32_e32 v21, 1.0, v21
	v_add_f32_e32 v16, 1.0, v16
	v_add_f32_e32 v19, 1.0, v19
	v_add_f32_e32 v20, 1.0, v20
	v_rcp_f32_e32 v22, v21
	v_add_f32_e32 v21, 1.0, v23
	v_add_f32_e32 v23, 1.0, v24
	v_rcp_f32_e32 v16, v16
	v_rcp_f32_e32 v17, v17
	v_rcp_f32_e32 v20, v20
	v_rcp_f32_e32 v21, v21
	v_rcp_f32_e32 v23, v23
	v_rcp_f32_e32 v19, v19
	v_pk_mul_f32 v[12:13], v[12:13], v[16:17]
	v_pk_mul_f32 v[14:15], v[14:15], v[20:21]
	v_pk_mul_f32 v[10:11], v[10:11], v[22:23]
	v_pk_mul_f32 v[8:9], v[8:9], v[18:19]
.LBB0_226:
	v_lshlrev_b64 v[16:17], 14, v[146:147]
	v_lshl_add_u64 v[16:17], s[10:11], 0, v[16:17]
	v_lshl_add_u64 v[16:17], v[148:149], 1, v[16:17]
	v_cvt_pk_bf16_f32 v12, v12, v13
	v_cvt_pk_bf16_f32 v13, v14, v15
	v_cvt_pk_bf16_f32 v14, v8, v9
	v_add_co_u32_e32 v8, vcc, 0x2c0000, v16
	v_cvt_pk_bf16_f32 v15, v10, v11
	s_nop 0
	v_addc_co_u32_e32 v9, vcc, 0, v17, vcc
	s_and_b64 vcc, exec, s[4:5]
	global_store_dwordx4 v[8:9], v[12:15], off nt
	s_cbranch_vccnz .LBB0_228
	v_mul_f32_e32 v9, 0xbfb8aa3b, v0
	v_mul_f32_e32 v10, 0xbfb8aa3b, v5
	v_exp_f32_e32 v9, v9
	v_exp_f32_e32 v11, v10
	v_mul_f32_e32 v13, 0xbfb8aa3b, v2
	v_mul_f32_e32 v14, 0xbfb8aa3b, v7
	v_add_f32_e32 v9, 1.0, v9
	v_mul_f32_e32 v8, 0xbfb8aa3b, v4
	v_rcp_f32_e32 v10, v9
	v_add_f32_e32 v9, 1.0, v11
	v_mul_f32_e32 v11, 0xbfb8aa3b, v1
	v_mul_f32_e32 v12, 0xbfb8aa3b, v6
	v_exp_f32_e32 v13, v13
	v_exp_f32_e32 v15, v14
	v_mul_f32_e32 v14, 0xbfb8aa3b, v3
	v_exp_f32_e32 v8, v8
	v_exp_f32_e32 v11, v11
	v_exp_f32_e32 v12, v12
	v_exp_f32_e32 v18, v14
	v_add_f32_e32 v13, 1.0, v13
	v_add_f32_e32 v8, 1.0, v8
	v_add_f32_e32 v11, 1.0, v11
	v_add_f32_e32 v12, 1.0, v12
	v_rcp_f32_e32 v14, v13
	v_add_f32_e32 v13, 1.0, v15
	v_add_f32_e32 v15, 1.0, v18
	v_rcp_f32_e32 v8, v8
	v_rcp_f32_e32 v9, v9
	v_rcp_f32_e32 v12, v12
	v_rcp_f32_e32 v13, v13
	v_rcp_f32_e32 v15, v15
	v_rcp_f32_e32 v11, v11
	v_pk_mul_f32 v[4:5], v[4:5], v[8:9]
	v_pk_mul_f32 v[6:7], v[6:7], v[12:13]
	v_pk_mul_f32 v[2:3], v[2:3], v[14:15]
	v_pk_mul_f32 v[0:1], v[0:1], v[10:11]
.LBB0_228:
	v_lshl_add_u64 v[8:9], v[16:17], 0, s[64:65]
	v_cvt_pk_bf16_f32 v4, v4, v5
	v_cvt_pk_bf16_f32 v5, v6, v7
	v_cvt_pk_bf16_f32 v6, v0, v1
	v_cvt_pk_bf16_f32 v7, v2, v3
	global_store_dwordx4 v[8:9], v[4:7], off offset:256 nt
	s_andn2_b64 vcc, exec, s[0:1]
	s_mov_b64 s[0:1], -1
	s_cbranch_vccnz .LBB0_184
	s_branch .LBB0_233

.LBB0_235:
	v_or_b32_e32 v150, 16, v146
	v_ashrrev_i32_e32 v147, 31, v146
	v_ashrrev_i32_e32 v151, 31, v150
	v_lshlrev_b64 v[148:149], 7, v[146:147]
	v_lshlrev_b64 v[150:151], 7, v[150:151]
	v_lshl_add_u64 v[148:149], v[136:137], 0, v[148:149]
	v_lshl_add_u64 v[150:151], v[136:137], 0, v[150:151]
	global_store_dwordx4 v[148:149], v[124:127], off nt
	global_store_dwordx4 v[148:149], v[120:123], off offset:16 nt
	global_store_dwordx4 v[150:151], v[108:111], off nt
	global_store_dwordx4 v[150:151], v[104:107], off offset:16 nt
	v_or_b32_e32 v150, 32, v146
	v_ashrrev_i32_e32 v151, 31, v150
	v_lshlrev_b64 v[150:151], 7, v[150:151]
	v_lshl_add_u64 v[150:151], v[136:137], 0, v[150:151]
	global_store_dwordx4 v[150:151], v[92:95], off nt
	global_store_dwordx4 v[150:151], v[88:91], off offset:16 nt
	v_or_b32_e32 v150, 48, v146
	v_ashrrev_i32_e32 v151, 31, v150
	v_lshlrev_b64 v[150:151], 7, v[150:151]
	s_movk_i32 s4, 0x4000
	v_lshl_add_u64 v[150:151], v[136:137], 0, v[150:151]
	v_add_co_u32_e32 v160, vcc, s4, v148
	global_store_dwordx4 v[150:151], v[76:79], off nt
	global_store_dwordx4 v[150:151], v[72:75], off offset:16 nt
	v_lshl_add_u64 v[150:151], v[148:149], 0, s[50:51]
	v_addc_co_u32_e32 v161, vcc, 0, v149, vcc
	global_store_dwordx4 v[160:161], v[60:63], off nt
	global_store_dwordx4 v[150:151], v[56:59], off offset:16 nt
	v_lshl_add_u64 v[150:151], v[148:149], 0, s[52:53]
	global_store_dwordx4 v[160:161], v[44:47], off offset:2048 nt
	global_store_dwordx4 v[150:151], v[40:43], off offset:16 nt
	v_add_co_u32_e32 v160, vcc, 0x5000, v148
	v_lshl_add_u64 v[150:151], v[148:149], 0, s[54:55]
	s_nop 0
	v_addc_co_u32_e32 v161, vcc, 0, v149, vcc
	global_store_dwordx4 v[160:161], v[28:31], off nt
	global_store_dwordx4 v[150:151], v[24:27], off offset:16 nt
	v_lshl_add_u64 v[148:149], v[148:149], 0, s[56:57]
	global_store_dwordx4 v[160:161], v[12:15], off offset:2048 nt
	global_store_dwordx4 v[148:149], v[8:11], off offset:16 nt
	s_cbranch_execnz .LBB0_232
	s_branch .LBB0_196

.LBB0_560:
	s_waitcnt vmcnt(0)
	s_cmp_gt_u32 s12, 30
	s_cbranch_scc1 .LBB0_562
	s_waitcnt vmcnt(6)
	v_lshl_add_u64 v[60:61], v[76:77], 0, s[0:1]
	v_add_co_u32_e32 v0, vcc, 0x2110000, v60
	v_lshl_add_u64 v[56:57], v[78:79], 0, s[0:1]
	s_nop 0
	v_addc_co_u32_e32 v1, vcc, 0, v61, vcc
	v_add_co_u32_e32 v4, vcc, 0x4010000, v56
	s_waitcnt vmcnt(5)
	v_lshl_add_u64 v[64:65], s[26:27], 0, v[74:75]
	v_addc_co_u32_e32 v5, vcc, 0, v57, vcc
	v_add_co_u32_e32 v8, vcc, 0x1b910000, v60
	global_load_dwordx4 v[0:3], v[0:1], off
	s_nop 0
	v_addc_co_u32_e32 v9, vcc, 0, v61, vcc
	v_add_co_u32_e32 v12, vcc, 0x2111000, v60
	global_load_dwordx4 v[4:7], v[4:5], off
	s_nop 0
	v_addc_co_u32_e32 v13, vcc, 0, v61, vcc
	v_add_co_u32_e32 v16, vcc, 0x4011000, v56
	global_load_dwordx4 v[8:11], v[8:9], off
	s_nop 0
	global_load_dwordx4 v[12:15], v[12:13], off
	v_addc_co_u32_e32 v17, vcc, 0, v57, vcc
	v_add_co_u32_e32 v24, vcc, 0x1b911000, v60
	global_load_dwordx4 v[16:19], v[16:17], off
	s_nop 0
	v_addc_co_u32_e32 v25, vcc, 0, v61, vcc
	v_add_co_u32_e32 v40, vcc, 0x2112000, v60
	s_nop 1
	v_addc_co_u32_e32 v41, vcc, 0, v61, vcc
	v_add_co_u32_e32 v44, vcc, 0x4012000, v56
	global_load_dwordx4 v[24:27], v[24:25], off
	s_nop 0
	global_load_dwordx4 v[40:43], v[40:41], off
	v_addc_co_u32_e32 v45, vcc, 0, v57, vcc
	v_add_co_u32_e32 v48, vcc, 0x1b912000, v60
	global_load_dwordx4 v[44:47], v[44:45], off
	s_nop 0
	v_addc_co_u32_e32 v49, vcc, 0, v61, vcc
	v_add_co_u32_e32 v52, vcc, 0x2113000, v60
	s_nop 1
	v_addc_co_u32_e32 v53, vcc, 0, v61, vcc
	v_add_co_u32_e32 v56, vcc, 0x4013000, v56
	global_load_dwordx4 v[48:51], v[48:49], off
	s_nop 0
	global_load_dwordx4 v[52:55], v[52:53], off
	v_addc_co_u32_e32 v57, vcc, 0, v57, vcc
	v_add_co_u32_e32 v60, vcc, 0x1b913000, v60
	global_load_dwordx4 v[56:59], v[56:57], off
	s_nop 0
	v_addc_co_u32_e32 v61, vcc, 0, v61, vcc
	v_add_co_u32_e32 v66, vcc, 0x6108000, v64
	global_load_dwordx4 v[60:63], v[60:61], off
	s_nop 0
	v_addc_co_u32_e32 v67, vcc, 0, v65, vcc
	s_waitcnt vmcnt(16)
	v_add_co_u32_e32 v68, vcc, 0x6109000, v64
	s_nop 1
	v_addc_co_u32_e32 v69, vcc, 0, v65, vcc
	global_load_dwordx4 v[64:67], v[66:67], off
	s_nop 0
	global_load_dwordx4 v[68:71], v[68:69], off
.LBB0_562:
	s_andn2_b32 s4, 1, s12
	s_mulk_i32 s4, 0x4400
	v_add_u32_e32 v84, s4, v96
	ds_read_b128 v[98:101], v84 offset:32
	ds_read_b128 v[102:105], v84
	ds_read_b128 v[106:109], v84 offset:16
	ds_read_b128 v[86:89], v84 offset:48
	ds_read_b128 v[110:113], v95
	ds_read_b128 v[114:117], v95 offset:16
	ds_read_b128 v[118:121], v95 offset:32
	ds_read_b128 v[122:125], v95 offset:48
	s_waitcnt lgkmcnt(7)
	v_lshlrev_b32_e32 v194, 16, v98
	s_waitcnt lgkmcnt(6)
	v_lshlrev_b32_e32 v148, 16, v103
	v_and_b32_e32 v149, 0xffff0000, v103
	v_lshlrev_b32_e32 v156, 16, v102
	v_and_b32_e32 v157, 0xffff0000, v102
	v_lshlrev_b32_e32 v144, 16, v104
	v_and_b32_e32 v145, 0xffff0000, v104
	v_pk_mul_f32 v[150:151], v[148:149], v[148:149]
	v_pk_mul_f32 v[102:103], v[156:157], v[156:157]
	v_lshlrev_b32_e32 v140, 16, v105
	v_and_b32_e32 v141, 0xffff0000, v105
	v_pk_mul_f32 v[104:105], v[144:145], v[144:145]
	v_add_f32_e32 v97, v150, v151
	v_add_f32_e32 v102, v102, v103
	v_pk_mul_f32 v[142:143], v[140:141], v[140:141]
	s_waitcnt lgkmcnt(5)
	v_lshlrev_b32_e32 v176, 16, v106
	v_and_b32_e32 v177, 0xffff0000, v106
	v_add_f32_e32 v97, v102, v97
	v_add_f32_e32 v102, v104, v105
	v_lshlrev_b32_e32 v170, 16, v107
	v_and_b32_e32 v171, 0xffff0000, v107
	v_pk_mul_f32 v[106:107], v[176:177], v[176:177]
	v_add_f32_e32 v97, v102, v97
	v_add_f32_e32 v102, v142, v143
	v_lshlrev_b32_e32 v166, 16, v108
	v_and_b32_e32 v167, 0xffff0000, v108
	v_pk_mul_f32 v[172:173], v[170:171], v[170:171]
	v_add_f32_e32 v97, v102, v97
	v_add_f32_e32 v102, v106, v107
	v_lshlrev_b32_e32 v162, 16, v109
	v_and_b32_e32 v163, 0xffff0000, v109
	v_pk_mul_f32 v[108:109], v[166:167], v[166:167]
	v_add_f32_e32 v97, v102, v97
	v_add_f32_e32 v102, v172, v173
	v_pk_mul_f32 v[164:165], v[162:163], v[162:163]
	v_and_b32_e32 v195, 0xffff0000, v98
	v_add_f32_e32 v97, v102, v97
	v_add_f32_e32 v102, v108, v109
	v_lshlrev_b32_e32 v190, 16, v99
	v_and_b32_e32 v191, 0xffff0000, v99
	v_pk_mul_f32 v[98:99], v[194:195], v[194:195]
	v_add_f32_e32 v97, v102, v97
	v_add_f32_e32 v102, v164, v165
	v_and_b32_e32 v131, 0xffff0000, v101
	v_and_b32_e32 v130, 0xffff0000, v100
	v_pk_mul_f32 v[192:193], v[190:191], v[190:191]
	v_add_f32_e32 v97, v102, v97
	v_add_f32_e32 v98, v98, v99
	v_lshlrev_b32_e32 v127, 16, v101
	v_lshlrev_b32_e32 v126, 16, v100
	v_pk_mul_f32 v[84:85], v[130:131], v[130:131]
	v_add_f32_e32 v97, v98, v97
	v_add_f32_e32 v98, v192, v193
	v_pk_fma_f32 v[100:101], v[126:127], v[126:127], v[84:85]
	s_waitcnt lgkmcnt(4)
	v_and_b32_e32 v135, 0xffff0000, v87
	v_and_b32_e32 v134, 0xffff0000, v86
	v_add_f32_e32 v97, v98, v97
	v_lshlrev_b32_e32 v133, 16, v87
	v_lshlrev_b32_e32 v132, 16, v86
	v_pk_mul_f32 v[84:85], v[134:135], v[134:135]
	v_add_f32_e32 v97, v100, v97
	v_pk_fma_f32 v[136:137], v[132:133], v[132:133], v[84:85]
	v_lshlrev_b32_e32 v87, 16, v89
	v_lshlrev_b32_e32 v86, 16, v88
	v_and_b32_e32 v89, 0xffff0000, v89
	v_and_b32_e32 v88, 0xffff0000, v88
	v_add_f32_e32 v97, v101, v97
	v_pk_mul_f32 v[84:85], v[88:89], v[88:89]
	v_add_f32_e32 v97, v136, v97
	v_pk_fma_f32 v[138:139], v[86:87], v[86:87], v[84:85]
	v_add_f32_e32 v97, v137, v97
	v_add_f32_e32 v97, v138, v97
	v_add_f32_e32 v97, v139, v97
	v_lshlrev_b32_e32 v152, 16, v33
	v_and_b32_e32 v153, 0xffff0000, v33
	v_add_f32_dpp v97, v97, v97 quad_perm:[1,0,3,2] row_mask:0xf bank_mask:0xf bound_ctrl:1
	v_lshlrev_b32_e32 v158, 16, v32
	v_and_b32_e32 v159, 0xffff0000, v32
	v_add_f32_dpp v97, v97, v97 quad_perm:[2,3,0,1] row_mask:0xf bank_mask:0xf bound_ctrl:1
	v_fmamk_f32 v97, v97, 0x3c000000, v178
	v_rsq_f32_e32 v136, v97
	v_lshlrev_b32_e32 v146, 16, v34
	v_and_b32_e32 v147, 0xffff0000, v34
	v_lshlrev_b32_e32 v160, 16, v35
	v_pk_mul_f32 v[106:107], v[136:137], v[156:157] op_sel_hi:[0,1]
	v_pk_mul_f32 v[108:109], v[136:137], v[148:149] op_sel_hi:[0,1]
	s_waitcnt lgkmcnt(3)
	v_pk_mul_f32 v[106:107], v[110:111], v[106:107]
	v_pk_mul_f32 v[108:109], v[112:113], v[108:109]
	v_pk_mul_f32 v[106:107], v[106:107], v[158:159]
	v_pk_mul_f32 v[108:109], v[108:109], v[152:153]
	v_cvt_pk_bf16_f32 v106, v106, v107
	v_cvt_pk_bf16_f32 v107, v108, v109
	v_pk_mul_f32 v[108:109], v[136:137], v[144:145] op_sel_hi:[0,1]
	v_pk_mul_f32 v[110:111], v[136:137], v[140:141] op_sel_hi:[0,1]
	v_and_b32_e32 v161, 0xffff0000, v35
	s_waitcnt lgkmcnt(2)
	v_pk_mul_f32 v[108:109], v[114:115], v[108:109]
	v_pk_mul_f32 v[110:111], v[116:117], v[110:111]
	v_pk_mul_f32 v[108:109], v[108:109], v[146:147]
	v_pk_mul_f32 v[110:111], v[110:111], v[160:161]
	v_lshl_add_u64 v[84:85], s[26:27], 0, v[82:83]
	v_cvt_pk_bf16_f32 v108, v108, v109
	v_cvt_pk_bf16_f32 v109, v110, v111
	ds_read_b128 v[98:101], v95 offset:64
	ds_read_b128 v[102:105], v95 offset:80
	global_store_dwordx4 v[84:85], v[106:109], off
	v_lshlrev_b32_e32 v174, 16, v37
	v_and_b32_e32 v175, 0xffff0000, v37
	v_pk_mul_f32 v[106:107], v[136:137], v[176:177] op_sel_hi:[0,1]
	v_pk_mul_f32 v[108:109], v[136:137], v[170:171] op_sel_hi:[0,1]
	v_lshlrev_b32_e32 v186, 16, v36
	v_and_b32_e32 v187, 0xffff0000, v36
	s_waitcnt lgkmcnt(3)
	v_pk_mul_f32 v[106:107], v[118:119], v[106:107]
	v_pk_mul_f32 v[108:109], v[120:121], v[108:109]
	v_pk_mul_f32 v[106:107], v[106:107], v[186:187]
	v_pk_mul_f32 v[108:109], v[108:109], v[174:175]
	v_cvt_pk_bf16_f32 v106, v106, v107
	v_cvt_pk_bf16_f32 v107, v108, v109
	v_pk_mul_f32 v[108:109], v[136:137], v[166:167] op_sel_hi:[0,1]
	v_pk_mul_f32 v[110:111], v[136:137], v[162:163] op_sel_hi:[0,1]
	v_lshlrev_b32_e32 v168, 16, v38
	v_and_b32_e32 v169, 0xffff0000, v38
	v_lshlrev_b32_e32 v188, 16, v39
	v_and_b32_e32 v189, 0xffff0000, v39
	s_waitcnt lgkmcnt(2)
	v_pk_mul_f32 v[108:109], v[122:123], v[108:109]
	v_pk_mul_f32 v[110:111], v[124:125], v[110:111]
	v_pk_mul_f32 v[108:109], v[108:109], v[168:169]
	v_pk_mul_f32 v[110:111], v[110:111], v[188:189]
	v_cvt_pk_bf16_f32 v108, v108, v109
	v_cvt_pk_bf16_f32 v109, v110, v111
	global_store_dwordx4 v[84:85], v[106:109], off offset:16
	v_lshlrev_b32_e32 v138, 16, v28
	v_and_b32_e32 v139, 0xffff0000, v28
	v_pk_mul_f32 v[106:107], v[136:137], v[194:195] op_sel_hi:[0,1]
	s_waitcnt lgkmcnt(1)
	v_pk_mul_f32 v[98:99], v[98:99], v[106:107]
	v_pk_mul_f32 v[106:107], v[136:137], v[190:191] op_sel_hi:[0,1]
	v_pk_mul_f32 v[100:101], v[100:101], v[106:107]
	v_lshlrev_b32_e32 v106, 16, v29
	v_and_b32_e32 v107, 0xffff0000, v29
	v_pk_mul_f32 v[98:99], v[98:99], v[138:139]
	v_pk_mul_f32 v[100:101], v[100:101], v[106:107]
	v_cvt_pk_bf16_f32 v98, v98, v99
	v_cvt_pk_bf16_f32 v99, v100, v101
	v_mov_b32_e32 v100, v126
	v_mov_b32_e32 v101, v130
	v_pk_mul_f32 v[100:101], v[136:137], v[100:101] op_sel_hi:[0,1]
	s_waitcnt lgkmcnt(0)
	v_pk_mul_f32 v[100:101], v[102:103], v[100:101]
	v_lshlrev_b32_e32 v102, 16, v30
	v_and_b32_e32 v103, 0xffff0000, v30
	v_mov_b32_e32 v130, v127
	v_pk_mul_f32 v[100:101], v[100:101], v[102:103]
	v_pk_mul_f32 v[102:103], v[136:137], v[130:131] op_sel_hi:[0,1]
	v_pk_mul_f32 v[102:103], v[104:105], v[102:103]
	v_lshlrev_b32_e32 v104, 16, v31
	v_and_b32_e32 v105, 0xffff0000, v31
	v_pk_mul_f32 v[102:103], v[102:103], v[104:105]
	v_cvt_pk_bf16_f32 v100, v100, v101
	v_cvt_pk_bf16_f32 v101, v102, v103
	global_store_dwordx4 v[84:85], v[98:101], off offset:32
	ds_read_b128 v[98:101], v95 offset:96
	ds_read_b128 v[102:105], v95 offset:112
	v_mov_b32_e32 v106, v132
	v_mov_b32_e32 v107, v134
	v_pk_mul_f32 v[106:107], v[136:137], v[106:107] op_sel_hi:[0,1]
	s_waitcnt lgkmcnt(1)
	v_pk_mul_f32 v[98:99], v[98:99], v[106:107]
	v_lshlrev_b32_e32 v106, 16, v20
	v_and_b32_e32 v107, 0xffff0000, v20
	v_mov_b32_e32 v134, v133
	v_pk_mul_f32 v[98:99], v[98:99], v[106:107]
	v_pk_mul_f32 v[106:107], v[136:137], v[134:135] op_sel_hi:[0,1]
	v_pk_mul_f32 v[100:101], v[100:101], v[106:107]
	v_lshlrev_b32_e32 v106, 16, v21
	v_and_b32_e32 v107, 0xffff0000, v21
	v_pk_mul_f32 v[100:101], v[100:101], v[106:107]
	v_cvt_pk_bf16_f32 v98, v98, v99
	v_cvt_pk_bf16_f32 v99, v100, v101
	v_mov_b32_e32 v100, v86
	v_mov_b32_e32 v101, v88
	v_mov_b32_e32 v88, v87
	v_pk_mul_f32 v[100:101], v[136:137], v[100:101] op_sel_hi:[0,1]
	v_pk_mul_f32 v[86:87], v[136:137], v[88:89] op_sel_hi:[0,1]
	s_waitcnt lgkmcnt(0)
	v_pk_mul_f32 v[100:101], v[102:103], v[100:101]
	v_lshlrev_b32_e32 v102, 16, v22
	v_and_b32_e32 v103, 0xffff0000, v22
	v_pk_mul_f32 v[86:87], v[104:105], v[86:87]
	v_lshlrev_b32_e32 v88, 16, v23
	v_and_b32_e32 v89, 0xffff0000, v23
	v_pk_mul_f32 v[100:101], v[100:101], v[102:103]
	v_pk_mul_f32 v[86:87], v[86:87], v[88:89]
	v_cvt_pk_bf16_f32 v100, v100, v101
	v_cvt_pk_bf16_f32 v101, v86, v87
	global_store_dwordx4 v[84:85], v[98:101], off offset:48
	s_cmp_lt_i32 s12, 33
	s_cbranch_scc1 .LBB0_564
	s_cmp_lg_u32 s12, 33
	s_cselect_b64 s[4:5], -1, 0
	s_cbranch_execz .LBB0_565
	s_branch .LBB0_566

.LBB0_592:
	s_waitcnt lgkmcnt(0)
	s_barrier
	s_cmp_eq_u32 s12, 33
	s_cbranch_scc1 .LBB0_595
	s_waitcnt vmcnt(0)
	s_cmp_gt_u32 s12, 31
	s_cbranch_scc1 .Lscan_pf_skip
	global_load_dwordx2 v[214:215], v[166:167], off offset:-64
	global_load_dwordx2 v[216:217], v[166:167], off offset:-48
	global_load_dwordx2 v[218:219], v[166:167], off offset:-32
	global_load_dwordx2 v[220:221], v[166:167], off offset:-16
	global_load_dwordx2 v[222:223], v[166:167], off
	global_load_dwordx2 v[224:225], v[166:167], off offset:16
	global_load_dwordx2 v[226:227], v[166:167], off offset:32
	global_load_dwordx2 v[228:229], v[166:167], off offset:48
	global_load_dword v230, v129, s[0:1]
.Lscan_pf_skip:
	s_and_b32 s3, s12, 1
	s_mul_i32 s4, s3, 0xea00
	s_add_i32 s4, s4, 0
	v_add3_u32 v68, s4, v155, v128
	v_add_u32_e32 v69, 0x2000, v68
	ds_read2_b64 v[232:235], v68 offset1:2
	ds_read2_b64 v[236:239], v69 offset0:32 offset1:34
	ds_read2_b64 v[240:243], v68 offset0:4 offset1:6
	ds_read2_b64 v[248:251], v69 offset0:36 offset1:38
	ds_read2_b64 v[252:255], v68 offset0:8 offset1:10
	v_cvt_pk_bf16_f32 v80, v16, v17
	v_cvt_pk_bf16_f32 v81, v18, v19
	v_cvt_pk_bf16_f32 v82, v20, v21
	v_cvt_pk_bf16_f32 v83, v22, v23
	v_cvt_pk_bf16_f32 v172, v24, v25
	v_cvt_pk_bf16_f32 v173, v26, v27
	v_cvt_pk_bf16_f32 v174, v28, v29
	s_waitcnt lgkmcnt(4)
	v_mfma_f32_32x32x16_bf16 v[112:127], v[232:235], v[80:83], 0
	ds_read2_b64 v[232:235], v69 offset0:40 offset1:42
	v_cvt_pk_bf16_f32 v175, v30, v31
	v_cvt_pk_bf16_f32 v186, v32, v33
	v_cvt_pk_bf16_f32 v187, v34, v35
	v_cvt_pk_bf16_f32 v188, v36, v37
	v_cvt_pk_bf16_f32 v189, v38, v39
	v_cvt_pk_bf16_f32 v190, v40, v41
	v_cvt_pk_bf16_f32 v191, v42, v43
	s_waitcnt lgkmcnt(4)
	v_mfma_f32_32x32x16_bf16 v[96:111], v[236:239], v[80:83], 0
	ds_read2_b64 v[236:239], v68 offset0:12 offset1:14
	v_cvt_pk_bf16_f32 v192, v44, v45
	v_cvt_pk_bf16_f32 v193, v46, v47
	v_cvt_pk_bf16_f32 v130, v48, v49
	v_cvt_pk_bf16_f32 v131, v50, v51
	v_cvt_pk_bf16_f32 v132, v52, v53
	v_cvt_pk_bf16_f32 v133, v54, v55
	s_waitcnt lgkmcnt(4)
	v_mfma_f32_32x32x16_bf16 v[112:127], v[240:243], v[172:175], v[112:127]
	ds_read2_b64 v[240:243], v69 offset0:44 offset1:46
	v_cvt_pk_bf16_f32 v142, v56, v57
	v_cvt_pk_bf16_f32 v143, v58, v59
	v_cvt_pk_bf16_f32 v144, v60, v61
	v_cvt_pk_bf16_f32 v145, v62, v63
	v_cvt_pk_bf16_f32 v138, v0, v1
	v_cvt_pk_bf16_f32 v139, v2, v3
	s_waitcnt lgkmcnt(4)
	v_mfma_f32_32x32x16_bf16 v[96:111], v[248:251], v[172:175], v[96:111]
	ds_read2_b64 v[248:251], v69 offset0:48 offset1:50
	v_cvt_pk_bf16_f32 v140, v4, v5
	v_cvt_pk_bf16_f32 v141, v6, v7
	v_cvt_pk_bf16_f32 v134, v8, v9
	v_cvt_pk_bf16_f32 v135, v10, v11
	v_cvt_pk_bf16_f32 v136, v12, v13
	v_cvt_pk_bf16_f32 v137, v14, v15
	s_waitcnt lgkmcnt(4)
	v_mfma_f32_32x32x16_bf16 v[112:127], v[252:255], v[186:189], v[112:127]
	ds_read2_b64 v[252:255], v69 offset0:52 offset1:54
	v_add_u32_e32 v171, 0x4000, v68
	v_add_u32_e32 v176, 0x6000, v68
	v_and_b32_e32 v177, 0xffff0000, v146
	v_pk_mul_f32 v[30:31], v[30:31], v[156:157] op_sel_hi:[1,0]
	v_pk_mul_f32 v[28:29], v[28:29], v[156:157] op_sel_hi:[1,0]
	v_pk_mul_f32 v[26:27], v[26:27], v[156:157] op_sel_hi:[1,0]
	s_waitcnt lgkmcnt(4)
	v_mfma_f32_32x32x16_bf16 v[96:111], v[232:235], v[186:189], v[96:111]
	ds_read2_b64 v[232:235], v69 offset0:56 offset1:58
	v_mul_f32_e64 v24, v24, v156
	v_mul_f32_e64 v25, v25, v156
	v_mul_f32_e64 v22, v22, v156
	v_mul_f32_e64 v23, v23, v156
	v_pk_mul_f32 v[20:21], v[20:21], v[156:157] op_sel_hi:[1,0]
	v_pk_mul_f32 v[18:19], v[18:19], v[156:157] op_sel_hi:[1,0]
	v_pk_mul_f32 v[16:17], v[16:17], v[156:157] op_sel_hi:[1,0]
	v_pk_mul_f32 v[46:47], v[46:47], v[156:157] op_sel_hi:[1,0]
	s_waitcnt lgkmcnt(4)
	v_mfma_f32_32x32x16_bf16 v[112:127], v[236:239], v[190:193], v[112:127]
	ds_read2_b64 v[236:239], v69 offset0:60 offset1:62
	v_mul_f32_e64 v44, v44, v156
	v_mul_f32_e64 v45, v45, v156
	v_mul_f32_e64 v42, v42, v156
	v_mul_f32_e64 v43, v43, v156
	v_pk_mul_f32 v[40:41], v[40:41], v[156:157] op_sel_hi:[1,0]
	v_pk_mul_f32 v[38:39], v[38:39], v[156:157] op_sel_hi:[1,0]
	v_pk_mul_f32 v[36:37], v[36:37], v[156:157] op_sel_hi:[1,0]
	s_waitcnt lgkmcnt(4)
	v_mfma_f32_32x32x16_bf16 v[96:111], v[240:243], v[190:193], v[96:111]
	ds_read2_b64 v[240:243], v68 offset0:16 offset1:18
	v_mul_f32_e64 v34, v34, v156
	v_mul_f32_e64 v35, v35, v156
	v_mul_f32_e64 v32, v32, v156
	v_mul_f32_e64 v33, v33, v156
	v_pk_mul_f32 v[62:63], v[62:63], v[156:157] op_sel_hi:[1,0]
	v_pk_mul_f32 v[60:61], v[60:61], v[156:157] op_sel_hi:[1,0]
	v_pk_mul_f32 v[58:59], v[58:59], v[156:157] op_sel_hi:[1,0]
	v_pk_mul_f32 v[56:57], v[56:57], v[156:157] op_sel_hi:[1,0]
	s_waitcnt lgkmcnt(4)
	v_mfma_f32_32x32x16_bf16 v[96:111], v[248:251], v[130:133], v[96:111]
	ds_read2_b64 v[248:251], v68 offset0:20 offset1:22
	v_mul_f32_e64 v54, v54, v156
	v_mul_f32_e64 v55, v55, v156
	v_mul_f32_e64 v52, v52, v156
	v_mul_f32_e64 v53, v53, v156
	v_pk_mul_f32 v[50:51], v[50:51], v[156:157] op_sel_hi:[1,0]
	v_pk_mul_f32 v[48:49], v[48:49], v[156:157] op_sel_hi:[1,0]
	v_pk_mul_f32 v[14:15], v[14:15], v[156:157] op_sel_hi:[1,0]
	v_pk_mul_f32 v[12:13], v[12:13], v[156:157] op_sel_hi:[1,0]
	s_waitcnt lgkmcnt(4)
	v_mfma_f32_32x32x16_bf16 v[96:111], v[252:255], v[142:145], v[96:111]
	ds_read2_b64 v[252:255], v68 offset0:24 offset1:26
	v_mul_f32_e64 v10, v10, v156
	v_mul_f32_e64 v11, v11, v156
	v_mul_f32_e64 v8, v8, v156
	v_mul_f32_e64 v9, v9, v156
	v_pk_mul_f32 v[6:7], v[6:7], v[156:157] op_sel_hi:[1,0]
	v_pk_mul_f32 v[4:5], v[4:5], v[156:157] op_sel_hi:[1,0]
	v_pk_mul_f32 v[2:3], v[2:3], v[156:157] op_sel_hi:[1,0]
	v_pk_mul_f32 v[0:1], v[0:1], v[156:157] op_sel_hi:[1,0]
	s_waitcnt lgkmcnt(4)
	v_mfma_f32_32x32x16_bf16 v[96:111], v[232:235], v[138:141], v[96:111]
	ds_read2_b64 v[232:235], v68 offset0:28 offset1:30
	s_cmp_gt_u32 s12, 31
	s_waitcnt lgkmcnt(4)
	v_mfma_f32_32x32x16_bf16 v[96:111], v[236:239], v[134:137], v[96:111]
	ds_read2_b64 v[236:239], v171 offset0:64 offset1:66
	s_waitcnt lgkmcnt(4)
	v_mfma_f32_32x32x16_bf16 v[112:127], v[240:243], v[130:133], v[112:127]
	ds_read2_b64 v[240:243], v171 offset0:68 offset1:70
	s_waitcnt lgkmcnt(4)
	v_mfma_f32_32x32x16_bf16 v[112:127], v[248:251], v[142:145], v[112:127]
	ds_read2_b64 v[248:251], v176 offset0:96 offset1:98
	s_waitcnt lgkmcnt(4)
	v_mfma_f32_32x32x16_bf16 v[112:127], v[252:255], v[138:141], v[112:127]
	ds_read2_b64 v[252:255], v176 offset0:100 offset1:102
	s_waitcnt lgkmcnt(4)
	v_mfma_f32_32x32x16_bf16 v[112:127], v[232:235], v[134:137], v[112:127]
	ds_read2_b64 v[232:235], v171 offset0:72 offset1:74
	s_waitcnt lgkmcnt(4)
	v_mfma_f32_32x32x16_bf16 v[64:79], v[236:239], v[80:83], 0
	ds_read2_b64 v[236:239], v176 offset0:104 offset1:106
	s_waitcnt lgkmcnt(4)
	v_mfma_f32_32x32x16_bf16 v[64:79], v[240:243], v[172:175], v[64:79]
	ds_read2_b64 v[240:243], v171 offset0:76 offset1:78
	s_waitcnt lgkmcnt(4)
	v_mfma_f32_32x32x16_bf16 v[80:95], v[248:251], v[80:83], 0
	ds_read2_b64 v[248:251], v176 offset0:108 offset1:110
	s_waitcnt lgkmcnt(4)
	v_mfma_f32_32x32x16_bf16 v[80:95], v[252:255], v[172:175], v[80:95]
	ds_read2_b64 v[252:255], v171 offset0:80 offset1:82
	s_waitcnt lgkmcnt(4)
	v_mfma_f32_32x32x16_bf16 v[64:79], v[232:235], v[186:189], v[64:79]
	ds_read2_b64 v[232:235], v171 offset0:84 offset1:86
	s_waitcnt lgkmcnt(4)
	v_mfma_f32_32x32x16_bf16 v[80:95], v[236:239], v[186:189], v[80:95]
	ds_read2_b64 v[236:239], v171 offset0:88 offset1:90
	s_waitcnt lgkmcnt(4)
	v_mfma_f32_32x32x16_bf16 v[64:79], v[240:243], v[190:193], v[64:79]
	ds_read2_b64 v[240:243], v176 offset0:112 offset1:114
	s_waitcnt lgkmcnt(4)
	v_mfma_f32_32x32x16_bf16 v[80:95], v[248:251], v[190:193], v[80:95]
	ds_read2_b64 v[248:251], v176 offset0:116 offset1:118
	s_waitcnt lgkmcnt(4)
	v_mfma_f32_32x32x16_bf16 v[64:79], v[252:255], v[130:133], v[64:79]
	ds_read2_b64 v[252:255], v176 offset0:120 offset1:122
	s_waitcnt lgkmcnt(4)
	v_mfma_f32_32x32x16_bf16 v[64:79], v[232:235], v[142:145], v[64:79]
	ds_read2_b64 v[232:235], v171 offset0:92 offset1:94
	s_waitcnt lgkmcnt(4)
	v_mfma_f32_32x32x16_bf16 v[64:79], v[236:239], v[138:141], v[64:79]
	ds_read2_b64 v[236:239], v176 offset0:124 offset1:126
	v_add3_u32 v171, s4, v169, v128
	v_add_u32_e32 v176, 0x9000, v171
	v_add_u32_e32 v171, 0x8000, v171
	s_waitcnt lgkmcnt(4)
	v_mfma_f32_32x32x16_bf16 v[80:95], v[240:243], v[130:133], v[80:95]
	s_waitcnt lgkmcnt(3)
	v_mfma_f32_32x32x16_bf16 v[80:95], v[248:251], v[142:145], v[80:95]
	v_lshlrev_b32_e32 v142, 16, v148
	v_and_b32_e32 v143, 0xffff0000, v148
	v_add_f32_e64 v142, v142, -v96
	v_add_f32_e64 v143, v143, -v97
	v_lshlrev_b32_e32 v96, 16, v149
	v_and_b32_e32 v97, 0xffff0000, v149
	v_pk_add_f32 v[144:145], v[96:97], v[98:99] neg_lo:[0,1] neg_hi:[0,1]
	v_lshlrev_b32_e32 v96, 16, v158
	s_waitcnt lgkmcnt(2)
	v_mfma_f32_32x32x16_bf16 v[80:95], v[252:255], v[138:141], v[80:95]
	v_and_b32_e32 v97, 0xffff0000, v158
	v_add_f32_e64 v98, v96, -v116
	v_add_f32_e64 v99, v97, -v117
	v_lshlrev_b32_e32 v96, 16, v159
	v_and_b32_e32 v97, 0xffff0000, v159
	v_pk_add_f32 v[116:117], v[96:97], v[118:119] neg_lo:[0,1] neg_hi:[0,1]
	v_cvt_pk_bf16_f32 v98, v98, v99
	v_cvt_pk_bf16_f32 v99, v116, v117
	s_waitcnt lgkmcnt(1)
	v_mfma_f32_32x32x16_bf16 v[64:79], v[232:235], v[134:137], v[64:79]
	ds_read2_b64 v[172:175], v176 offset0:164 offset1:166
	ds_read2_b64 v[202:205], v176 offset0:168 offset1:170
	ds_read2_b64 v[206:209], v171 offset0:128 offset1:130
	ds_read2_b64 v[210:213], v171 offset0:132 offset1:134
	ds_read2_b64 v[186:189], v176 offset0:160 offset1:162
	ds_read2_b64 v[130:133], v176 offset0:172 offset1:174
	v_lshlrev_b32_e32 v176, 16, v146
	v_pk_add_f32 v[112:113], v[176:177], v[112:113] neg_lo:[0,1] neg_hi:[0,1]
	v_lshlrev_b32_e32 v176, 16, v147
	v_and_b32_e32 v177, 0xffff0000, v147
	v_pk_add_f32 v[114:115], v[176:177], v[114:115] neg_lo:[0,1] neg_hi:[0,1]
	s_waitcnt lgkmcnt(6)
	v_mfma_f32_32x32x16_bf16 v[80:95], v[236:239], v[134:137], v[80:95]
	v_lshlrev_b32_e32 v134, 16, v162
	v_and_b32_e32 v135, 0xffff0000, v162
	v_cvt_pk_bf16_f32 v97, v114, v115
	v_lshlrev_b32_e32 v114, 16, v163
	v_and_b32_e32 v115, 0xffff0000, v163
	v_lshlrev_b32_e32 v116, 16, v164
	v_and_b32_e32 v117, 0xffff0000, v164
	v_lshlrev_b32_e32 v118, 16, v150
	v_and_b32_e32 v119, 0xffff0000, v150
	v_cvt_pk_bf16_f32 v96, v112, v113
	v_pk_add_f32 v[112:113], v[134:135], v[120:121] neg_lo:[0,1] neg_hi:[0,1]
	v_pk_add_f32 v[114:115], v[114:115], v[122:123] neg_lo:[0,1] neg_hi:[0,1]
	v_pk_add_f32 v[116:117], v[116:117], v[124:125] neg_lo:[0,1] neg_hi:[0,1]
	v_lshlrev_b32_e32 v120, 16, v165
	v_and_b32_e32 v121, 0xffff0000, v165
	v_cvt_pk_bf16_f32 v112, v112, v113
	v_cvt_pk_bf16_f32 v113, v114, v115
	v_cvt_pk_bf16_f32 v114, v116, v117
	v_pk_add_f32 v[116:117], v[118:119], v[100:101] neg_lo:[0,1] neg_hi:[0,1]
	v_lshlrev_b32_e32 v100, 16, v151
	v_and_b32_e32 v101, 0xffff0000, v151
	v_pk_add_f32 v[120:121], v[120:121], v[126:127] neg_lo:[0,1] neg_hi:[0,1]
	v_pk_add_f32 v[118:119], v[100:101], v[102:103] neg_lo:[0,1] neg_hi:[0,1]
	v_add3_u32 v126, s4, v157, v168
	v_cvt_pk_bf16_f32 v115, v120, v121
	v_cvt_pk_bf16_f32 v102, v116, v117
	v_cvt_pk_bf16_f32 v103, v118, v119
	ds_read_b64_tr_b16 v[116:117], v126 offset:42496
	ds_read_b64_tr_b16 v[118:119], v126 offset:44672
	ds_read_b64_tr_b16 v[122:123], v126 offset:44736
	ds_read_b64_tr_b16 v[120:121], v126 offset:42560
	s_waitcnt lgkmcnt(2)
	v_mfma_f32_32x32x16_bf16 v[16:31], v[116:119], v[96:99], v[16:31]
	v_cvt_pk_bf16_f32 v100, v142, v143
	v_cvt_pk_bf16_f32 v101, v144, v145
	v_lshlrev_b32_e32 v124, 16, v152
	v_and_b32_e32 v125, 0xffff0000, v152
	s_waitcnt lgkmcnt(0)
	v_mfma_f32_32x32x16_bf16 v[32:47], v[120:123], v[96:99], v[32:47]
	ds_read_b64_tr_b16 v[116:117], v126 offset:46848
	ds_read_b64_tr_b16 v[118:119], v126 offset:49024
	ds_read_b64_tr_b16 v[122:123], v126 offset:49088
	ds_read_b64_tr_b16 v[120:121], v126 offset:46912
	s_waitcnt lgkmcnt(2)
	v_mfma_f32_32x32x16_bf16 v[16:31], v[116:119], v[112:115], v[16:31]
	ds_read_b64_tr_b16 v[116:117], v126 offset:51200
	ds_read_b64_tr_b16 v[118:119], v126 offset:53376
	s_waitcnt lgkmcnt(2)
	v_mfma_f32_32x32x16_bf16 v[32:47], v[120:123], v[112:115], v[32:47]
	v_add_f32_e64 v120, v124, -v104
	v_add_f32_e64 v121, v125, -v105
	v_lshlrev_b32_e32 v104, 16, v153
	v_and_b32_e32 v105, 0xffff0000, v153
	v_add_f32_e64 v122, v104, -v106
	v_add_f32_e64 v123, v105, -v107
	ds_read_b64_tr_b16 v[106:107], v126 offset:53440
	ds_read_b64_tr_b16 v[104:105], v126 offset:51264
	v_lshlrev_b32_e32 v124, 16, v161
	v_and_b32_e32 v125, 0xffff0000, v161
	s_waitcnt lgkmcnt(2)
	v_mfma_f32_32x32x16_bf16 v[16:31], v[116:119], v[100:103], v[16:31]
	v_lshlrev_b32_e32 v116, 16, v160
	v_and_b32_e32 v117, 0xffff0000, v160
	v_add_f32_e64 v108, v116, -v108
	v_add_f32_e64 v109, v117, -v109
	ds_read_b64_tr_b16 v[116:117], v126 offset:55552
	ds_read_b64_tr_b16 v[118:119], v126 offset:57728
	v_pk_add_f32 v[110:111], v[124:125], v[110:111] neg_lo:[0,1] neg_hi:[0,1]
	s_waitcnt lgkmcnt(2)
	v_mfma_f32_32x32x16_bf16 v[32:47], v[104:107], v[100:103], v[32:47]
	v_cvt_pk_bf16_f32 v104, v120, v121
	v_cvt_pk_bf16_f32 v105, v122, v123
	v_cvt_pk_bf16_f32 v106, v108, v109
	v_cvt_pk_bf16_f32 v107, v110, v111
	ds_read_b64_tr_b16 v[110:111], v126 offset:57792
	ds_read_b64_tr_b16 v[108:109], v126 offset:55616
	s_waitcnt lgkmcnt(2)
	v_mfma_f32_32x32x16_bf16 v[16:31], v[116:119], v[104:107], v[16:31]
	ds_read_b64_tr_b16 v[116:117], v126 offset:42624
	ds_read_b64_tr_b16 v[118:119], v126 offset:44800
	ds_read_b64_tr_b16 v[122:123], v126 offset:44864
	ds_read_b64_tr_b16 v[120:121], v126 offset:42688
	v_mfma_f32_32x32x16_bf16 v[80:95], v[186:189], v[96:99], v[80:95]
	s_waitcnt lgkmcnt(2)
	v_mfma_f32_32x32x16_bf16 v[48:63], v[116:119], v[96:99], v[48:63]
	s_waitcnt lgkmcnt(0)
	v_mfma_f32_32x32x16_bf16 v[0:15], v[120:123], v[96:99], v[0:15]
	v_mfma_f32_32x32x16_bf16 v[64:79], v[206:209], v[96:99], v[64:79]
	v_mfma_f32_32x32x16_bf16 v[32:47], v[108:111], v[104:107], v[32:47]
	ds_read_b64_tr_b16 v[96:97], v126 offset:46976
	ds_read_b64_tr_b16 v[98:99], v126 offset:49152
	ds_read_b64_tr_b16 v[110:111], v126 offset:49216
	ds_read_b64_tr_b16 v[108:109], v126 offset:47040
	v_mfma_f32_32x32x16_bf16 v[80:95], v[172:175], v[112:115], v[80:95]
	s_waitcnt lgkmcnt(2)
	v_mfma_f32_32x32x16_bf16 v[48:63], v[96:99], v[112:115], v[48:63]
	s_waitcnt lgkmcnt(0)
	v_mfma_f32_32x32x16_bf16 v[0:15], v[108:111], v[112:115], v[0:15]
	ds_read_b64_tr_b16 v[96:97], v126 offset:51328
	ds_read_b64_tr_b16 v[98:99], v126 offset:53504
	ds_read_b64_tr_b16 v[110:111], v126 offset:53568
	ds_read_b64_tr_b16 v[108:109], v126 offset:51392
	v_mfma_f32_32x32x16_bf16 v[80:95], v[202:205], v[100:103], v[80:95]
	s_waitcnt lgkmcnt(2)
	v_mfma_f32_32x32x16_bf16 v[48:63], v[96:99], v[100:103], v[48:63]
	s_waitcnt lgkmcnt(0)
	v_mfma_f32_32x32x16_bf16 v[0:15], v[108:111], v[100:103], v[0:15]
	ds_read_b64_tr_b16 v[96:97], v126 offset:55680
	ds_read_b64_tr_b16 v[98:99], v126 offset:57856
	ds_read_b64_tr_b16 v[102:103], v126 offset:57920
	ds_read_b64_tr_b16 v[100:101], v126 offset:55744
	v_mfma_f32_32x32x16_bf16 v[64:79], v[210:213], v[112:115], v[64:79]
	s_waitcnt lgkmcnt(2)
	v_mfma_f32_32x32x16_bf16 v[48:63], v[96:99], v[104:107], v[48:63]
	s_waitcnt lgkmcnt(0)
	v_mfma_f32_32x32x16_bf16 v[0:15], v[100:103], v[104:107], v[0:15]
	v_mfma_f32_32x32x16_bf16 v[80:95], v[130:133], v[104:107], v[80:95]
	s_cbranch_scc1 .LBB0_591
	s_waitcnt vmcnt(0)
	v_mov_b64_e32 v[146:147], v[214:215]
	v_mov_b64_e32 v[158:159], v[216:217]
	v_mov_b64_e32 v[162:163], v[218:219]
	v_mov_b64_e32 v[164:165], v[220:221]
	v_mov_b64_e32 v[148:149], v[222:223]
	v_mov_b64_e32 v[150:151], v[224:225]
	v_mov_b64_e32 v[152:153], v[226:227]
	v_mov_b64_e32 v[160:161], v[228:229]
	v_mov_b32_e32 v156, v230
	s_branch .LBB0_591

.LBB0_695:
	v_lshl_add_u32 v152, s36, 8, v146
	v_lshl_or_b32 v154, s67, 8, v148
	v_ashrrev_i32_e32 v153, 31, v152
	v_ashrrev_i32_e32 v155, 31, v154
	v_lshlrev_b64 v[156:157], 12, v[152:153]
	v_lshl_add_u64 v[156:157], s[10:11], 0, v[156:157]
	v_lshlrev_b64 v[154:155], 1, v[154:155]
	v_lshl_add_u64 v[156:157], v[156:157], 0, v[154:155]
	v_cvt_pk_bf16_f32 v60, v60, v61
	v_cvt_pk_bf16_f32 v61, v62, v63
	v_cvt_pk_bf16_f32 v62, v56, v57
	v_add_co_u32_e32 v56, vcc, s63, v156
	v_cvt_pk_bf16_f32 v68, v68, v69
	v_cvt_pk_bf16_f32 v69, v70, v71
	v_cvt_pk_bf16_f32 v70, v64, v65
	v_lshl_add_u64 v[64:65], v[156:157], 0, s[4:5]
	v_addc_co_u32_e32 v57, vcc, 0, v157, vcc
	v_cvt_pk_bf16_f32 v44, v44, v45
	v_cvt_pk_bf16_f32 v45, v46, v47
	v_cvt_pk_bf16_f32 v46, v40, v41
	v_cvt_pk_bf16_f32 v47, v42, v43
	v_cvt_pk_bf16_f32 v108, v108, v109
	v_cvt_pk_bf16_f32 v109, v110, v111
	v_cvt_pk_bf16_f32 v110, v104, v105
	v_or_b32_e32 v104, 16, v152
	global_store_dwordx4 v[64:65], v[44:47], off offset:256 sc1
	v_ashrrev_i32_e32 v105, 31, v104
	v_cvt_pk_bf16_f32 v92, v92, v93
	v_add_co_u32_e32 v46, vcc, s64, v156
	v_cvt_pk_bf16_f32 v93, v94, v95
	v_cvt_pk_bf16_f32 v94, v88, v89
	v_or_b32_e32 v88, 32, v152
	v_lshl_add_u64 v[44:45], v[156:157], 0, s[18:19]
	v_addc_co_u32_e32 v47, vcc, 0, v157, vcc
	v_cvt_pk_bf16_f32 v28, v28, v29
	v_cvt_pk_bf16_f32 v29, v30, v31
	v_cvt_pk_bf16_f32 v30, v24, v25
	v_cvt_pk_bf16_f32 v31, v26, v27
	v_lshlrev_b64 v[104:105], 12, v[104:105]
	v_ashrrev_i32_e32 v89, 31, v88
	v_cvt_pk_bf16_f32 v76, v76, v77
	v_cvt_pk_bf16_f32 v77, v78, v79
	v_cvt_pk_bf16_f32 v78, v72, v73
	v_or_b32_e32 v72, 48, v152
	global_store_dwordx4 v[44:45], v[28:31], off offset:256 sc1
	v_cvt_pk_bf16_f32 v111, v106, v107
	v_lshl_add_u64 v[104:105], s[10:11], 0, v[104:105]
	v_add_co_u32_e32 v30, vcc, s65, v156
	v_lshlrev_b64 v[88:89], 12, v[88:89]
	v_ashrrev_i32_e32 v73, 31, v72
	v_lshl_add_u64 v[28:29], v[156:157], 0, s[20:21]
	v_addc_co_u32_e32 v31, vcc, 0, v157, vcc
	v_cvt_pk_bf16_f32 v12, v12, v13
	v_cvt_pk_bf16_f32 v13, v14, v15
	v_cvt_pk_bf16_f32 v14, v8, v9
	v_cvt_pk_bf16_f32 v15, v10, v11
	global_store_dwordx4 v[156:157], v[108:111], off offset:256 sc1
	v_cvt_pk_bf16_f32 v95, v90, v91
	v_lshl_add_u64 v[88:89], s[10:11], 0, v[88:89]
	v_lshl_add_u64 v[108:109], v[104:105], 0, v[154:155]
	v_lshlrev_b64 v[72:73], 12, v[72:73]
	global_store_dwordx4 v[28:29], v[12:15], off offset:256 sc1
	global_store_dwordx4 v[108:109], v[92:95], off offset:256 sc1
	v_cvt_pk_bf16_f32 v79, v74, v75
	v_add_co_u32_e32 v14, vcc, s66, v156
	v_lshl_add_u64 v[92:93], v[88:89], 0, v[154:155]
	v_lshl_add_u64 v[72:73], s[10:11], 0, v[72:73]
	v_addc_co_u32_e32 v15, vcc, 0, v157, vcc
	v_cvt_pk_bf16_f32 v124, v124, v125
	v_cvt_pk_bf16_f32 v125, v126, v127
	v_cvt_pk_bf16_f32 v126, v120, v121
	v_cvt_pk_bf16_f32 v127, v122, v123
	v_cvt_pk_bf16_f32 v104, v116, v117
	v_cvt_pk_bf16_f32 v105, v118, v119
	v_cvt_pk_bf16_f32 v106, v112, v113
	v_cvt_pk_bf16_f32 v107, v114, v115
	v_cvt_pk_bf16_f32 v88, v100, v101
	v_cvt_pk_bf16_f32 v89, v102, v103
	v_cvt_pk_bf16_f32 v90, v96, v97
	v_cvt_pk_bf16_f32 v91, v98, v99
	global_store_dwordx4 v[92:93], v[76:79], off offset:256 sc1
	v_cvt_pk_bf16_f32 v74, v80, v81
	v_cvt_pk_bf16_f32 v75, v82, v83
	v_lshl_add_u64 v[76:77], v[72:73], 0, v[154:155]
	v_cvt_pk_bf16_f32 v72, v84, v85
	v_cvt_pk_bf16_f32 v73, v86, v87
	v_cvt_pk_bf16_f32 v71, v66, v67
	v_cvt_pk_bf16_f32 v63, v58, v59
	v_cvt_pk_bf16_f32 v40, v52, v53
	v_cvt_pk_bf16_f32 v41, v54, v55
	v_cvt_pk_bf16_f32 v42, v48, v49
	v_cvt_pk_bf16_f32 v43, v50, v51
	v_cvt_pk_bf16_f32 v24, v36, v37
	v_cvt_pk_bf16_f32 v25, v38, v39
	v_cvt_pk_bf16_f32 v26, v32, v33
	v_cvt_pk_bf16_f32 v27, v34, v35
	v_lshl_add_u64 v[12:13], v[156:157], 0, s[22:23]
	v_cvt_pk_bf16_f32 v8, v20, v21
	v_cvt_pk_bf16_f32 v9, v22, v23
	v_cvt_pk_bf16_f32 v10, v16, v17
	v_cvt_pk_bf16_f32 v11, v18, v19
	v_cvt_pk_bf16_f32 v4, v4, v5
	v_cvt_pk_bf16_f32 v5, v6, v7
	v_cvt_pk_bf16_f32 v6, v0, v1
	v_cvt_pk_bf16_f32 v7, v2, v3
	s_andn2_b64 vcc, exec, s[0:1]
	s_mov_b64 s[0:1], -1
	global_store_dwordx4 v[156:157], v[124:127], off sc1
	global_store_dwordx4 v[108:109], v[104:107], off sc1
	global_store_dwordx4 v[92:93], v[88:91], off sc1
	global_store_dwordx4 v[76:77], v[72:75], off sc1
	global_store_dwordx4 v[76:77], v[68:71], off offset:256 sc1
	global_store_dwordx4 v[56:57], v[60:63], off sc1
	global_store_dwordx4 v[46:47], v[40:43], off sc1
	global_store_dwordx4 v[30:31], v[24:27], off sc1
	global_store_dwordx4 v[14:15], v[8:11], off sc1
	global_store_dwordx4 v[12:13], v[4:7], off offset:256 sc1
	s_cbranch_vccnz .LBB0_684
	s_andn2_b64 vcc, exec, s[12:13]
	s_cbranch_vccnz .LBB0_683
	s_barrier
	s_branch .LBB0_683

	.amdhsa_kernel _Z9hymba_fwd6Params
		.amdhsa_group_segment_fixed_size 0
		.amdhsa_private_segment_fixed_size 0
		.amdhsa_kernarg_size 376
		.amdhsa_user_sgpr_count 2
		.amdhsa_user_sgpr_dispatch_ptr 0
		.amdhsa_user_sgpr_queue_ptr 0
		.amdhsa_user_sgpr_kernarg_segment_ptr 1
		.amdhsa_user_sgpr_dispatch_id 0
		.amdhsa_user_sgpr_kernarg_preload_length 0
		.amdhsa_user_sgpr_kernarg_preload_offset 0
		.amdhsa_user_sgpr_private_segment_size 0
		.amdhsa_uses_dynamic_stack 0
		.amdhsa_enable_private_segment 0
		.amdhsa_system_sgpr_workgroup_id_x 1
		.amdhsa_system_sgpr_workgroup_id_y 0
		.amdhsa_system_sgpr_workgroup_id_z 0
		.amdhsa_system_sgpr_workgroup_info 0
		.amdhsa_system_vgpr_workitem_id 2
		.amdhsa_next_free_vgpr 256
		.amdhsa_next_free_sgpr 100
		.amdhsa_accum_offset 256
		.amdhsa_reserve_vcc 1
		.amdhsa_float_round_mode_32 0
		.amdhsa_float_round_mode_16_64 0
		.amdhsa_float_denorm_mode_32 3
		.amdhsa_float_denorm_mode_16_64 3
		.amdhsa_dx10_clamp 1
		.amdhsa_ieee_mode 1
		.amdhsa_fp16_overflow 0
		.amdhsa_tg_split 0
		.amdhsa_exception_fp_ieee_invalid_op 0
		.amdhsa_exception_fp_denorm_src 0
		.amdhsa_exception_fp_ieee_div_zero 0
		.amdhsa_exception_fp_ieee_overflow 0
		.amdhsa_exception_fp_ieee_underflow 0
		.amdhsa_exception_fp_ieee_inexact 0
		.amdhsa_exception_int_div_zero 0
	.end_amdhsa_kernel

amdhsa.kernels:
  - .agpr_count:     0
    .args:
      - .offset:         0
        .size:           120
        .value_kind:     by_value
      - .offset:         120
        .size:           4
        .value_kind:     hidden_block_count_x
      - .offset:         124
        .size:           4
        .value_kind:     hidden_block_count_y
      - .offset:         128
        .size:           4
        .value_kind:     hidden_block_count_z
      - .offset:         132
        .size:           2
        .value_kind:     hidden_group_size_x
      - .offset:         134
        .size:           2
        .value_kind:     hidden_group_size_y
      - .offset:         136
        .size:           2
        .value_kind:     hidden_group_size_z
      - .offset:         138
        .size:           2
        .value_kind:     hidden_remainder_x
      - .offset:         140
        .size:           2
        .value_kind:     hidden_remainder_y
      - .offset:         142
        .size:           2
        .value_kind:     hidden_remainder_z
      - .offset:         160
        .size:           8
        .value_kind:     hidden_global_offset_x
      - .offset:         168
        .size:           8
        .value_kind:     hidden_global_offset_y
      - .offset:         176
        .size:           8
        .value_kind:     hidden_global_offset_z
      - .offset:         184
        .size:           2
        .value_kind:     hidden_grid_dims
      - .offset:         208
        .size:           8
        .value_kind:     hidden_multigrid_sync_arg
      - .offset:         240
        .size:           4
        .value_kind:     hidden_dynamic_lds_size
    .group_segment_fixed_size: 0
    .kernarg_segment_align: 8
    .kernarg_segment_size: 376
    .language:       OpenCL C
    .language_version:
      - 2
      - 0
    .max_flat_workgroup_size: 512
    .name:           _Z9hymba_fwd6Params
    .private_segment_fixed_size: 0
    .sgpr_count:     106
    .sgpr_spill_count: 4
    .symbol:         _Z9hymba_fwd6Params.kd
    .uniform_work_group_size: 1
    .uses_dynamic_stack: false
    .vgpr_count:     256
    .vgpr_spill_count: 0
    .wavefront_size: 64
